# attention softmax: scalar reference-moved flag, cross-half max only in rescale path
# baseline (speedup 1.0000x reference)
; template <class AP, class BP, class Epi>
; DI void mfma_gemm_big_tile(const AP& aptr, const BP& bptr, int m0, int n0, int K, const Epi& epi, bf16* lds) {
;     ...
; #pragma unroll
;   for (int i = 0; i < 8; ++i)
; #pragma unroll
;     for (int j = 0; j < 4; ++j) epi(m0 + wm + 16 * i + l16, n0 + wn + 16 * j + 4 * lq, acc[i][j]);
;   asm volatile("s_waitcnt vmcnt(0)" ::: "memory");
;   __syncthreads();
.LBB0_247:
	v_and_b32_e32 v131, 15, v172
	v_bfe_u32 v130, v172, 4, 2
	s_add_i32 s0, s10, s17
	s_add_i32 s1, s11, s12
	v_add_u32_e32 v131, s0, v131
	v_and_b32_e32 v132, 1, v130
	v_lshrrev_b32_e32 v130, 1, v130
	v_lshlrev_b32_e32 v132, 4, v132
	v_lshl_add_u32 v130, v130, 3, v132
	v_add_u32_e32 v130, s1, v130
	v_mul_u32_u24_e32 v131, 0x1400, v131
	v_lshl_add_u32 v133, v130, 1, v131
	v_cvt_pk_bf16_f32 v216, v126, v127
	v_cvt_pk_bf16_f32 v217, v128, v129
	v_cvt_pk_bf16_f32 v218, v122, v123
	v_cvt_pk_bf16_f32 v219, v124, v125
	s_nop 1
	v_permlane16_swap_b32_e32 v216, v218
	v_permlane16_swap_b32_e32 v217, v219
	global_store_dwordx4 v133, v[216:219], s[62:63] offset:0
	v_cvt_pk_bf16_f32 v220, v118, v119
	v_cvt_pk_bf16_f32 v221, v120, v121
	v_cvt_pk_bf16_f32 v222, v114, v115
	v_cvt_pk_bf16_f32 v223, v116, v117
	s_nop 1
	v_permlane16_swap_b32_e32 v220, v222
	v_permlane16_swap_b32_e32 v221, v223
	global_store_dwordx4 v133, v[220:223], s[62:63] offset:64
	v_add_u32_e32 v133, 0x14000, v133
	v_cvt_pk_bf16_f32 v224, v110, v111
	v_cvt_pk_bf16_f32 v225, v112, v113
	v_cvt_pk_bf16_f32 v226, v106, v107
	v_cvt_pk_bf16_f32 v227, v108, v109
	s_nop 1
	v_permlane16_swap_b32_e32 v224, v226
	v_permlane16_swap_b32_e32 v225, v227
	global_store_dwordx4 v133, v[224:227], s[62:63] offset:0
	v_cvt_pk_bf16_f32 v228, v102, v103
	v_cvt_pk_bf16_f32 v229, v104, v105
	v_cvt_pk_bf16_f32 v230, v98, v99
	v_cvt_pk_bf16_f32 v231, v100, v101
	s_nop 1
	v_permlane16_swap_b32_e32 v228, v230
	v_permlane16_swap_b32_e32 v229, v231
	global_store_dwordx4 v133, v[228:231], s[62:63] offset:64
	v_add_u32_e32 v133, 0x14000, v133
	v_cvt_pk_bf16_f32 v232, v94, v95
	v_cvt_pk_bf16_f32 v233, v96, v97
	v_cvt_pk_bf16_f32 v234, v90, v91
	v_cvt_pk_bf16_f32 v235, v92, v93
	s_nop 1
	v_permlane16_swap_b32_e32 v232, v234
	v_permlane16_swap_b32_e32 v233, v235
	global_store_dwordx4 v133, v[232:235], s[62:63] offset:0
	v_cvt_pk_bf16_f32 v236, v86, v87
	v_cvt_pk_bf16_f32 v237, v88, v89
	v_cvt_pk_bf16_f32 v238, v82, v83
	v_cvt_pk_bf16_f32 v239, v84, v85
	s_nop 1
	v_permlane16_swap_b32_e32 v236, v238
	v_permlane16_swap_b32_e32 v237, v239
	global_store_dwordx4 v133, v[236:239], s[62:63] offset:64
	v_add_u32_e32 v133, 0x14000, v133
	v_cvt_pk_bf16_f32 v240, v78, v79
	v_cvt_pk_bf16_f32 v241, v80, v81
	v_cvt_pk_bf16_f32 v242, v74, v75
	v_cvt_pk_bf16_f32 v243, v76, v77
	s_nop 1
	v_permlane16_swap_b32_e32 v240, v242
	v_permlane16_swap_b32_e32 v241, v243
	global_store_dwordx4 v133, v[240:243], s[62:63] offset:0
	v_cvt_pk_bf16_f32 v244, v70, v71
	v_cvt_pk_bf16_f32 v245, v72, v73
	v_cvt_pk_bf16_f32 v246, v66, v67
	v_cvt_pk_bf16_f32 v247, v68, v69
	s_nop 1
	v_permlane16_swap_b32_e32 v244, v246
	v_permlane16_swap_b32_e32 v245, v247
	global_store_dwordx4 v133, v[244:247], s[62:63] offset:64
	v_add_u32_e32 v133, 0x14000, v133
	v_cvt_pk_bf16_f32 v216, v62, v63
	v_cvt_pk_bf16_f32 v217, v64, v65
	v_cvt_pk_bf16_f32 v218, v58, v59
	v_cvt_pk_bf16_f32 v219, v60, v61
	s_nop 1
	v_permlane16_swap_b32_e32 v216, v218
	v_permlane16_swap_b32_e32 v217, v219
	global_store_dwordx4 v133, v[216:219], s[62:63] offset:0
	v_cvt_pk_bf16_f32 v220, v54, v55
	v_cvt_pk_bf16_f32 v221, v56, v57
	v_cvt_pk_bf16_f32 v222, v50, v51
	v_cvt_pk_bf16_f32 v223, v52, v53
	s_nop 1
	v_permlane16_swap_b32_e32 v220, v222
	v_permlane16_swap_b32_e32 v221, v223
	global_store_dwordx4 v133, v[220:223], s[62:63] offset:64
	v_add_u32_e32 v133, 0x14000, v133
	v_cvt_pk_bf16_f32 v224, v46, v47
	v_cvt_pk_bf16_f32 v225, v48, v49
	v_cvt_pk_bf16_f32 v226, v42, v43
	v_cvt_pk_bf16_f32 v227, v44, v45
	s_nop 1
	v_permlane16_swap_b32_e32 v224, v226
	v_permlane16_swap_b32_e32 v225, v227
	global_store_dwordx4 v133, v[224:227], s[62:63] offset:0
	v_cvt_pk_bf16_f32 v228, v38, v39
	v_cvt_pk_bf16_f32 v229, v40, v41
	v_cvt_pk_bf16_f32 v230, v34, v35
	v_cvt_pk_bf16_f32 v231, v36, v37
	s_nop 1
	v_permlane16_swap_b32_e32 v228, v230
	v_permlane16_swap_b32_e32 v229, v231
	global_store_dwordx4 v133, v[228:231], s[62:63] offset:64
	v_add_u32_e32 v133, 0x14000, v133
	v_cvt_pk_bf16_f32 v232, v30, v31
	v_cvt_pk_bf16_f32 v233, v32, v33
	v_cvt_pk_bf16_f32 v234, v26, v27
	v_cvt_pk_bf16_f32 v235, v28, v29
	s_nop 1
	v_permlane16_swap_b32_e32 v232, v234
	v_permlane16_swap_b32_e32 v233, v235
	global_store_dwordx4 v133, v[232:235], s[62:63] offset:0
	v_cvt_pk_bf16_f32 v236, v22, v23
	v_cvt_pk_bf16_f32 v237, v24, v25
	v_cvt_pk_bf16_f32 v238, v18, v19
	v_cvt_pk_bf16_f32 v239, v20, v21
	s_nop 1
	v_permlane16_swap_b32_e32 v236, v238
	v_permlane16_swap_b32_e32 v237, v239
	global_store_dwordx4 v133, v[236:239], s[62:63] offset:64
	v_add_u32_e32 v133, 0x14000, v133
	v_cvt_pk_bf16_f32 v240, v14, v15
	v_cvt_pk_bf16_f32 v241, v16, v17
	v_cvt_pk_bf16_f32 v242, v10, v11
	v_cvt_pk_bf16_f32 v243, v12, v13
	s_nop 1
	v_permlane16_swap_b32_e32 v240, v242
	v_permlane16_swap_b32_e32 v241, v243
	global_store_dwordx4 v133, v[240:243], s[62:63] offset:0
	v_cvt_pk_bf16_f32 v244, v6, v7
	v_cvt_pk_bf16_f32 v245, v8, v9
	v_cvt_pk_bf16_f32 v246, v2, v3
	v_cvt_pk_bf16_f32 v247, v4, v5
	s_nop 1
	v_permlane16_swap_b32_e32 v244, v246
	v_permlane16_swap_b32_e32 v245, v247
	global_store_dwordx4 v133, v[244:247], s[62:63] offset:64
	s_add_i32 s9, s9, s41
	s_cmp_ge_i32 s9, s8
	s_cbranch_scc1 .LBB0_256

; template <class AP, class BP, class Epi>
; DI void mfma_gemm_big_tile(const AP& aptr, const BP& bptr, int m0, int n0, int K, const Epi& epi, bf16* lds) {
;     ...
; #pragma unroll
;   for (int i = 0; i < 8; ++i)
; #pragma unroll
;     for (int j = 0; j < 4; ++j) epi(m0 + wm + 16 * i + l16, n0 + wn + 16 * j + 4 * lq, acc[i][j]);
;   asm volatile("s_waitcnt vmcnt(0)" ::: "memory");
;   __syncthreads();
.LBB0_507:
	v_and_b32_e32 v131, 15, v172
	v_bfe_u32 v130, v172, 4, 2
	s_add_i32 s0, s10, s16
	s_add_i32 s1, s11, s12
	v_add_u32_e32 v131, s0, v131
	v_and_b32_e32 v132, 1, v130
	v_lshrrev_b32_e32 v130, 1, v130
	v_lshlrev_b32_e32 v132, 4, v132
	v_lshl_add_u32 v130, v130, 3, v132
	v_add_u32_e32 v130, s1, v130
	v_mul_u32_u24_e32 v131, 0x1400, v131
	v_lshl_add_u32 v133, v130, 1, v131
	v_cvt_pk_bf16_f32 v216, v126, v127
	v_cvt_pk_bf16_f32 v217, v128, v129
	v_cvt_pk_bf16_f32 v218, v122, v123
	v_cvt_pk_bf16_f32 v219, v124, v125
	s_nop 1
	v_permlane16_swap_b32_e32 v216, v218
	v_permlane16_swap_b32_e32 v217, v219
	global_store_dwordx4 v133, v[216:219], s[62:63] offset:0
	v_cvt_pk_bf16_f32 v220, v118, v119
	v_cvt_pk_bf16_f32 v221, v120, v121
	v_cvt_pk_bf16_f32 v222, v114, v115
	v_cvt_pk_bf16_f32 v223, v116, v117
	s_nop 1
	v_permlane16_swap_b32_e32 v220, v222
	v_permlane16_swap_b32_e32 v221, v223
	global_store_dwordx4 v133, v[220:223], s[62:63] offset:64
	v_add_u32_e32 v133, 0x14000, v133
	v_cvt_pk_bf16_f32 v224, v110, v111
	v_cvt_pk_bf16_f32 v225, v112, v113
	v_cvt_pk_bf16_f32 v226, v106, v107
	v_cvt_pk_bf16_f32 v227, v108, v109
	s_nop 1
	v_permlane16_swap_b32_e32 v224, v226
	v_permlane16_swap_b32_e32 v225, v227
	global_store_dwordx4 v133, v[224:227], s[62:63] offset:0
	v_cvt_pk_bf16_f32 v228, v102, v103
	v_cvt_pk_bf16_f32 v229, v104, v105
	v_cvt_pk_bf16_f32 v230, v98, v99
	v_cvt_pk_bf16_f32 v231, v100, v101
	s_nop 1
	v_permlane16_swap_b32_e32 v228, v230
	v_permlane16_swap_b32_e32 v229, v231
	global_store_dwordx4 v133, v[228:231], s[62:63] offset:64
	v_add_u32_e32 v133, 0x14000, v133
	v_cvt_pk_bf16_f32 v232, v94, v95
	v_cvt_pk_bf16_f32 v233, v96, v97
	v_cvt_pk_bf16_f32 v234, v90, v91
	v_cvt_pk_bf16_f32 v235, v92, v93
	s_nop 1
	v_permlane16_swap_b32_e32 v232, v234
	v_permlane16_swap_b32_e32 v233, v235
	global_store_dwordx4 v133, v[232:235], s[62:63] offset:0
	v_cvt_pk_bf16_f32 v236, v86, v87
	v_cvt_pk_bf16_f32 v237, v88, v89
	v_cvt_pk_bf16_f32 v238, v82, v83
	v_cvt_pk_bf16_f32 v239, v84, v85
	s_nop 1
	v_permlane16_swap_b32_e32 v236, v238
	v_permlane16_swap_b32_e32 v237, v239
	global_store_dwordx4 v133, v[236:239], s[62:63] offset:64
	v_add_u32_e32 v133, 0x14000, v133
	v_cvt_pk_bf16_f32 v240, v78, v79
	v_cvt_pk_bf16_f32 v241, v80, v81
	v_cvt_pk_bf16_f32 v242, v74, v75
	v_cvt_pk_bf16_f32 v243, v76, v77
	s_nop 1
	v_permlane16_swap_b32_e32 v240, v242
	v_permlane16_swap_b32_e32 v241, v243
	global_store_dwordx4 v133, v[240:243], s[62:63] offset:0
	v_cvt_pk_bf16_f32 v244, v70, v71
	v_cvt_pk_bf16_f32 v245, v72, v73
	v_cvt_pk_bf16_f32 v246, v66, v67
	v_cvt_pk_bf16_f32 v247, v68, v69
	s_nop 1
	v_permlane16_swap_b32_e32 v244, v246
	v_permlane16_swap_b32_e32 v245, v247
	global_store_dwordx4 v133, v[244:247], s[62:63] offset:64
	v_add_u32_e32 v133, 0x14000, v133
	v_cvt_pk_bf16_f32 v216, v62, v63
	v_cvt_pk_bf16_f32 v217, v64, v65
	v_cvt_pk_bf16_f32 v218, v58, v59
	v_cvt_pk_bf16_f32 v219, v60, v61
	s_nop 1
	v_permlane16_swap_b32_e32 v216, v218
	v_permlane16_swap_b32_e32 v217, v219
	global_store_dwordx4 v133, v[216:219], s[62:63] offset:0
	v_cvt_pk_bf16_f32 v220, v54, v55
	v_cvt_pk_bf16_f32 v221, v56, v57
	v_cvt_pk_bf16_f32 v222, v50, v51
	v_cvt_pk_bf16_f32 v223, v52, v53
	s_nop 1
	v_permlane16_swap_b32_e32 v220, v222
	v_permlane16_swap_b32_e32 v221, v223
	global_store_dwordx4 v133, v[220:223], s[62:63] offset:64
	v_add_u32_e32 v133, 0x14000, v133
	v_cvt_pk_bf16_f32 v224, v46, v47
	v_cvt_pk_bf16_f32 v225, v48, v49
	v_cvt_pk_bf16_f32 v226, v42, v43
	v_cvt_pk_bf16_f32 v227, v44, v45
	s_nop 1
	v_permlane16_swap_b32_e32 v224, v226
	v_permlane16_swap_b32_e32 v225, v227
	global_store_dwordx4 v133, v[224:227], s[62:63] offset:0
	v_cvt_pk_bf16_f32 v228, v38, v39
	v_cvt_pk_bf16_f32 v229, v40, v41
	v_cvt_pk_bf16_f32 v230, v34, v35
	v_cvt_pk_bf16_f32 v231, v36, v37
	s_nop 1
	v_permlane16_swap_b32_e32 v228, v230
	v_permlane16_swap_b32_e32 v229, v231
	global_store_dwordx4 v133, v[228:231], s[62:63] offset:64
	v_add_u32_e32 v133, 0x14000, v133
	v_cvt_pk_bf16_f32 v232, v30, v31
	v_cvt_pk_bf16_f32 v233, v32, v33
	v_cvt_pk_bf16_f32 v234, v26, v27
	v_cvt_pk_bf16_f32 v235, v28, v29
	s_nop 1
	v_permlane16_swap_b32_e32 v232, v234
	v_permlane16_swap_b32_e32 v233, v235
	global_store_dwordx4 v133, v[232:235], s[62:63] offset:0
	v_cvt_pk_bf16_f32 v236, v22, v23
	v_cvt_pk_bf16_f32 v237, v24, v25
	v_cvt_pk_bf16_f32 v238, v18, v19
	v_cvt_pk_bf16_f32 v239, v20, v21
	s_nop 1
	v_permlane16_swap_b32_e32 v236, v238
	v_permlane16_swap_b32_e32 v237, v239
	global_store_dwordx4 v133, v[236:239], s[62:63] offset:64
	v_add_u32_e32 v133, 0x14000, v133
	v_cvt_pk_bf16_f32 v240, v14, v15
	v_cvt_pk_bf16_f32 v241, v16, v17
	v_cvt_pk_bf16_f32 v242, v10, v11
	v_cvt_pk_bf16_f32 v243, v12, v13
	s_nop 1
	v_permlane16_swap_b32_e32 v240, v242
	v_permlane16_swap_b32_e32 v241, v243
	global_store_dwordx4 v133, v[240:243], s[62:63] offset:0
	v_cvt_pk_bf16_f32 v244, v6, v7
	v_cvt_pk_bf16_f32 v245, v8, v9
	v_cvt_pk_bf16_f32 v246, v2, v3
	v_cvt_pk_bf16_f32 v247, v4, v5
	s_nop 1
	v_permlane16_swap_b32_e32 v244, v246
	v_permlane16_swap_b32_e32 v245, v247
	global_store_dwordx4 v133, v[244:247], s[62:63] offset:64
	s_add_i32 s9, s9, s41
	s_cmp_ge_i32 s9, s8
	s_cbranch_scc1 .LBB0_516

; DI void attn_item(const Ctx& c, int item, bf16* lds) {
;     ...
;   for (int kt = 0; kt < ntile; ++kt) {
;     bf16* Ks = lds + (kt & 1) * ATT_BUF;
;     bf16* Vs = Ks + 64 * AK_LD;
; #pragma unroll
;     for (int i = 0; i < 3; ++i) { const int ci = tid + 256 * i; const int row = ci / 12, cc = ci % 12; *(u32x4*)(Ks + row * AK_LD + cc * 8) = rk[i]; }
; #pragma unroll
;     for (int i = 0; i < 2; ++i) {
;       bf16* d = Vs + (vrow + 32 * i) * AV_LD + vcc;
;       *(u32x2*)(d) = u32x2{rv[i][0], rv[i][1]}; *(u32x2*)(d + 4) = u32x2{rv[i][2], rv[i][3]};
;     }
;     __syncthreads();
;     if (kt + 1 < ntile) {
;       const bf16* kn = Kb + (size_t)(kt + 1) * 64 * 96;
;       const bf16* vn = Vb + (kt + 1) * 64;
; #pragma unroll
;       for (int i = 0; i < 3; ++i) rk[i] = *(const u32x4*)(kn + (koff + 2048u * i));
; #pragma unroll
;       for (int i = 0; i < 2; ++i) rv[i] = *(const u32x4*)(vn + (voff + (unsigned)(32 * T) * i));
;     }
; #pragma unroll
;     for (int qs = 0; qs < 2; ++qs) {
;       __builtin_amdgcn_sched_barrier(0);
;       f32x16 st[2];
;       {
;         f32x16 zz;
; #pragma unroll
;         for (int i = 0; i < 16; ++i) zz[i] = 0.f;
; #pragma unroll
;         for (int mt = 0; mt < 2; ++mt)
; #pragma unroll
;           for (int s = 0; s < 6; ++s) {
;             const bf16x8 a = *(const bf16x8*)(Ks + (32 * mt + r) * AK_LD + 16 * s + 8 * hh);
;             const bf16x8 qb_ = (qs == 0) ? qf0[s] : *(const bf16x8*)(Qs + r * AK_LD + 16 * s + 8 * hh);
;             st[mt] = (s == 0) ? MFMA32(a, qb_, zz) : MFMA32(a, qb_, st[mt]);
;           }
;       }
;       if (__builtin_amdgcn_ballot_w64(m[qs] != 0.f) != 0ull) {
; #pragma unroll
;         for (int i = 0; i < 16; ++i) { st[0][i] -= m[qs]; st[1][i] -= m[qs]; }
;       }
;       float mx = st[0][0];
; #pragma unroll
;       for (int i = 1; i < 16; ++i) mx = fmaxf(mx, st[0][i]);
; #pragma unroll
;       for (int i = 0; i < 16; ++i) mx = fmaxf(mx, st[1][i]);
;       mx = xhalf_max(mx);
;       if (__builtin_amdgcn_ballot_w64((kt == 0) ? (fabsf(mx) > 16.f) : (mx > 16.f)) != 0ull) {
;         const float d = (kt == 0) ? mx : fmaxf(mx, 0.f);
;         const float alpha = __builtin_amdgcn_exp2f(-d);
;         m[qs] += d; lsum[qs] *= alpha;
; #pragma unroll
;         for (int i = 0; i < 16; ++i) { ot[qs][0][i] *= alpha; ot[qs][1][i] *= alpha; st[0][i] -= d; st[1][i] -= d; }
;       }
;       float ps = 0.f;
.Lattn_noprio:
	s_waitcnt lgkmcnt(0)
	ds_read_b128 v[228:231], v161 offset:44032
	ds_read_b128 v[232:235], v161 offset:44064
	ds_read_b128 v[236:239], v161 offset:44096
	ds_read_b128 v[240:243], v161 offset:44128
	ds_read_b128 v[244:247], v161 offset:44160
	ds_read_b128 v[248:251], v161 offset:44192
	v_mov_b32_e32 v203, v8
	v_lshlrev_b32_e32 v159, 1, v159
	v_add_u32_e32 v202, v202, v156
	v_add_u32_e32 v3, v192, v193
	v_add_u32_e32 v182, v196, v197
	v_lshl_add_u32 v184, v191, 1, v199
	v_lshl_add_u32 v159, v156, 1, v159
	s_mov_b32 s9, 0
	s_mov_b32 s12, 0
	s_mov_b64 s[10:11], s[88:89]
	s_mov_b64 s[2:3], s[88:89]
	s_waitcnt lgkmcnt(0)
	v_add_u32_e32 v161, v194, v195
	v_mov_b32_e32 v96, 0
	v_mov_b32_e32 v97, 0
	v_mov_b32_e32 v98, 0
	v_mov_b32_e32 v99, 0
	v_mov_b32_e32 v104, 0
	v_mov_b32_e32 v105, 0
	v_mov_b32_e32 v106, 0
	v_mov_b32_e32 v107, 0
	v_mov_b32_e32 v4, 0
	v_mov_b32_e32 v5, 0
	v_mov_b32_e32 v6, 0
	v_mov_b32_e32 v7, 0
	v_mov_b32_e32 v8, 0
	v_mov_b32_e32 v9, 0
	v_mov_b32_e32 v10, 0
	v_mov_b32_e32 v11, 0
	v_mov_b32_e32 v12, 0
	v_mov_b32_e32 v13, 0
	v_mov_b32_e32 v14, 0
	v_mov_b32_e32 v15, 0
	v_mov_b32_e32 v192, 0
	v_mov_b32_e32 v193, 0
	v_mov_b32_e32 v194, 0
	v_mov_b32_e32 v195, 0
	s_waitcnt vmcnt(0)
	ds_write_b128 v3, v[136:139] offset:0
	ds_write_b128 v161, v[140:143] offset:0
	ds_write_b128 v182, v[144:147] offset:0
	ds_write_b64 v184, v[148:149] offset:13312
	ds_write_b64 v184, v[150:151] offset:13320
	ds_write_b64 v184, v[152:153] offset:17664
	ds_write_b64 v184, v[154:155] offset:17672
	global_load_dwordx4 v[136:139], v166, s[10:11]
	global_load_dwordx4 v[140:143], v168, s[10:11]
	global_load_dwordx4 v[144:147], v170, s[10:11]
	global_load_dwordx4 v[148:151], v162, s[2:3]
	global_load_dwordx4 v[152:155], v164, s[2:3]
	s_add_u32 s10, s10, 0x3000
	s_addc_u32 s11, s11, 0
	s_add_u32 s2, s2, 0x80
	s_addc_u32 s3, s3, 0
	s_waitcnt lgkmcnt(0)
	s_barrier
	ds_read_b128 v[204:207], v159 offset:0
	ds_read_b128 v[208:211], v159 offset:32
	ds_read_b128 v[212:215], v159 offset:64
	ds_read_b128 v[216:219], v159 offset:96
	ds_read_b128 v[220:223], v159 offset:128
	ds_read_b128 v[224:227], v159 offset:160
	s_waitcnt lgkmcnt(5)
	v_mfma_f32_32x32x16_bf16 v[80:95], v[204:207], v[112:115], 0
	s_waitcnt lgkmcnt(4)
	v_mfma_f32_32x32x16_bf16 v[80:95], v[208:211], v[116:119], v[80:95]
	s_waitcnt lgkmcnt(3)
	v_mfma_f32_32x32x16_bf16 v[80:95], v[212:215], v[120:123], v[80:95]
	s_waitcnt lgkmcnt(2)
	v_mfma_f32_32x32x16_bf16 v[80:95], v[216:219], v[124:127], v[80:95]
	s_waitcnt lgkmcnt(1)
	v_mfma_f32_32x32x16_bf16 v[80:95], v[220:223], v[128:131], v[80:95]
	s_waitcnt lgkmcnt(0)
	v_mfma_f32_32x32x16_bf16 v[80:95], v[224:227], v[132:135], v[80:95]
.Lattn_loop:
	s_cmp_eq_u32 s1, 0
	s_cselect_b64 s[4:5], -1, 0
	v_mfma_f32_32x32x16_bf16 v[32:47], v[4:7], v[96:99], v[32:47]
	ds_read_b64 v[4:5], v202 offset:13312
	ds_read_b64 v[6:7], v202 offset:13328
	v_mfma_f32_32x32x16_bf16 v[16:31], v[8:11], v[96:99], v[16:31]
	s_cmp_eq_u32 s9, 0
	s_nop 4
	s_cbranch_scc1 .Lattn_00_A_nosub
	v_sub_f32_e32 v80, v80, v2
	v_sub_f32_e32 v81, v81, v2
	v_sub_f32_e32 v82, v82, v2
	v_sub_f32_e32 v83, v83, v2
	v_sub_f32_e32 v84, v84, v2
	v_sub_f32_e32 v85, v85, v2
	v_sub_f32_e32 v86, v86, v2
	v_sub_f32_e32 v87, v87, v2
	v_sub_f32_e32 v88, v88, v2
	v_sub_f32_e32 v89, v89, v2
	v_sub_f32_e32 v90, v90, v2
	v_sub_f32_e32 v91, v91, v2
	v_sub_f32_e32 v92, v92, v2
	v_sub_f32_e32 v93, v93, v2
	v_sub_f32_e32 v94, v94, v2
	v_sub_f32_e32 v95, v95, v2
.Lattn_00_A_nosub:
	v_max3_f32 v185, v80, v81, v82
	v_max3_f32 v185, v185, v83, v84
	v_max3_f32 v185, v185, v85, v86
	v_max3_f32 v185, v185, v87, v88
	v_max3_f32 v185, v185, v89, v90
	ds_read_b64 v[8:9], v202 offset:17664
	ds_read_b64 v[10:11], v202 offset:17680
	v_mfma_f32_32x32x16_bf16 v[32:47], v[12:15], v[104:107], v[32:47]
	v_max3_f32 v185, v185, v91, v92
	v_max3_f32 v185, v185, v93, v94
	v_max_f32_e32 v185, v185, v95
	v_cndmask_b32_e64 v191, v185, |v185|, s[4:5]
	v_cmp_lt_f32_e32 vcc, s33, v191
	s_cbranch_vccnz .Lattn_00_A_rare
.Lattn_00_A_back:
	ds_read_b64 v[12:13], v202 offset:13344
	ds_read_b64 v[14:15], v202 offset:13360
	v_mfma_f32_32x32x16_bf16 v[16:31], v[192:195], v[104:107], v[16:31]
	v_exp_f32_e32 v80, v80
	v_exp_f32_e32 v81, v81
	v_exp_f32_e32 v82, v82
	ds_read_b64 v[192:193], v202 offset:17696
	ds_read_b64 v[194:195], v202 offset:17712
	v_mfma_f32_32x32x16_bf16 v[96:111], v[204:207], v[228:231], 0
	v_exp_f32_e32 v83, v83
	v_exp_f32_e32 v84, v84
	v_exp_f32_e32 v85, v85
	ds_read_b128 v[204:207], v159 offset:6656
	v_mfma_f32_32x32x16_bf16 v[96:111], v[208:211], v[232:235], v[96:111]
	v_exp_f32_e32 v86, v86
	v_exp_f32_e32 v87, v87
	v_add_f32_e32 v0, v0, v80
	v_add_f32_e32 v0, v0, v81
	ds_read_b128 v[208:211], v159 offset:6688
	v_mfma_f32_32x32x16_bf16 v[96:111], v[212:215], v[236:239], v[96:111]
	v_add_f32_e32 v0, v0, v82
	v_add_f32_e32 v0, v0, v83
	v_add_f32_e32 v0, v0, v84
	v_add_f32_e32 v0, v0, v85
	v_add_f32_e32 v0, v0, v86
	v_add_f32_e32 v0, v0, v87
	ds_read_b128 v[212:215], v159 offset:6720
	v_mfma_f32_32x32x16_bf16 v[96:111], v[216:219], v[240:243], v[96:111]
	v_cvt_pk_bf16_f32 v80, v80, v81
	v_cvt_pk_bf16_f32 v81, v82, v83
	v_cvt_pk_bf16_f32 v82, v84, v85
	v_cvt_pk_bf16_f32 v83, v86, v87
	v_exp_f32_e32 v88, v88
	ds_read_b128 v[216:219], v159 offset:6752
	v_mfma_f32_32x32x16_bf16 v[96:111], v[220:223], v[244:247], v[96:111]
	v_exp_f32_e32 v89, v89
	v_exp_f32_e32 v90, v90
	v_exp_f32_e32 v91, v91
	ds_read_b128 v[220:223], v159 offset:6784
	v_mfma_f32_32x32x16_bf16 v[96:111], v[224:227], v[248:251], v[96:111]
	v_exp_f32_e32 v92, v92
	v_exp_f32_e32 v93, v93
	v_exp_f32_e32 v94, v94
	ds_read_b128 v[224:227], v159 offset:6816
	s_waitcnt lgkmcnt(12)
	v_mfma_f32_32x32x16_bf16 v[64:79], v[4:7], v[80:83], v[64:79]
	v_exp_f32_e32 v95, v95
	v_add_f32_e32 v0, v0, v88
	v_add_f32_e32 v0, v0, v89
	v_add_f32_e32 v0, v0, v90
	v_add_f32_e32 v0, v0, v91
	s_waitcnt vmcnt(0)
	ds_write_b128 v3, v[136:139] offset:22016
	s_waitcnt lgkmcnt(11)
	v_mfma_f32_32x32x16_bf16 v[48:63], v[8:11], v[80:83], v[48:63]
	v_add_f32_e32 v0, v0, v92
	v_add_f32_e32 v0, v0, v93
	v_add_f32_e32 v0, v0, v94
	v_add_f32_e32 v0, v0, v95
	v_cvt_pk_bf16_f32 v88, v88, v89
	v_cvt_pk_bf16_f32 v89, v90, v91
	ds_write_b128 v161, v[140:143] offset:22016
	s_waitcnt lgkmcnt(10)
	v_cvt_pk_bf16_f32 v90, v92, v93
	v_cvt_pk_bf16_f32 v91, v94, v95
	s_nop 1
	v_mfma_f32_32x32x16_bf16 v[64:79], v[12:15], v[88:91], v[64:79]
	s_cmp_eq_u32 s12, 0
	s_cbranch_scc1 .Lattn_00_B_nosub
	v_sub_f32_e32 v96, v96, v201
	v_sub_f32_e32 v97, v97, v201
	v_sub_f32_e32 v98, v98, v201
	v_sub_f32_e32 v99, v99, v201
	v_sub_f32_e32 v100, v100, v201
	v_sub_f32_e32 v101, v101, v201
	v_sub_f32_e32 v102, v102, v201
	v_sub_f32_e32 v103, v103, v201
	v_sub_f32_e32 v104, v104, v201
	v_sub_f32_e32 v105, v105, v201
	v_sub_f32_e32 v106, v106, v201
	v_sub_f32_e32 v107, v107, v201
	v_sub_f32_e32 v108, v108, v201
	v_sub_f32_e32 v109, v109, v201
	v_sub_f32_e32 v110, v110, v201
	v_sub_f32_e32 v111, v111, v201
; #define MFMA32(a, b, c) __builtin_amdgcn_mfma_f32_32x32x16_bf16((a), (b), (c), 0, 0, 0)
; DI void attn_item(const Ctx& c, int item, bf16* lds) {
;     ...
;       if (__builtin_amdgcn_ballot_w64(m[qs] != 0.f) != 0ull) {
; #pragma unroll
;         for (int i = 0; i < 16; ++i) { st[0][i] -= m[qs]; st[1][i] -= m[qs]; }
;       }
;       float mx = st[0][0];
; #pragma unroll
;       for (int i = 1; i < 16; ++i) mx = fmaxf(mx, st[0][i]);
; #pragma unroll
;       for (int i = 0; i < 16; ++i) mx = fmaxf(mx, st[1][i]);
;       mx = xhalf_max(mx);
;       if (__builtin_amdgcn_ballot_w64((kt == 0) ? (fabsf(mx) > 16.f) : (mx > 16.f)) != 0ull) {
;         const float d = (kt == 0) ? mx : fmaxf(mx, 0.f);
;         const float alpha = __builtin_amdgcn_exp2f(-d);
;         m[qs] += d; lsum[qs] *= alpha;
; #pragma unroll
;         for (int i = 0; i < 16; ++i) { ot[qs][0][i] *= alpha; ot[qs][1][i] *= alpha; st[0][i] -= d; st[1][i] -= d; }
;       }
;       float ps = 0.f;
; #pragma unroll
;       for (int sp = 0; sp < 4; ++sp) {
;         const int mt = sp >> 1, s2 = sp & 1;
;         float e[8];
; #pragma unroll
;         for (int j = 0; j < 8; ++j) { e[j] = __builtin_amdgcn_exp2f(st[mt][8 * s2 + j]); ps += e[j]; }
;         u32x4 pk;
;         pk[0] = pk2(e[0], e[1]); pk[1] = pk2(e[2], e[3]); pk[2] = pk2(e[4], e[5]); pk[3] = pk2(e[6], e[7]);
;         const bf16x8 pf = __builtin_bit_cast(bf16x8, pk);
; #pragma unroll
;         for (int vt = 0; vt < 2; ++vt) {
;           const bf16* vp = Vs + (32 * vt + r) * AV_LD + 32 * mt + 16 * s2 + 4 * hh;
;           const s16x4 lo = *(const s16x4*)(vp), hi = *(const s16x4*)(vp + 8);
;           const bf16x8 a = __builtin_shufflevector(lo, hi, 0, 1, 2, 3, 4, 5, 6, 7);
;           ot[qs][vt] = MFMA32(a, pf, ot[qs][vt]);
;         }
;       }
;       lsum[qs] += ps;
.Lattn_00_B_nosub:
	v_max3_f32 v185, v96, v97, v98
	v_max3_f32 v185, v185, v99, v100
	v_max3_f32 v185, v185, v101, v102
	v_max3_f32 v185, v185, v103, v104
	v_max3_f32 v185, v185, v105, v106
	ds_write_b128 v182, v[144:147] offset:22016
	s_waitcnt lgkmcnt(9)
	v_mfma_f32_32x32x16_bf16 v[48:63], v[192:195], v[88:91], v[48:63]
	v_max3_f32 v185, v185, v107, v108
	v_max3_f32 v185, v185, v109, v110
	v_max_f32_e32 v185, v185, v111
	v_cndmask_b32_e64 v191, v185, |v185|, s[4:5]
	v_cmp_lt_f32_e32 vcc, s33, v191
	s_cbranch_vccnz .Lattn_00_B_rare
.Lattn_00_B_back:
	ds_write_b64 v184, v[148:149] offset:35328
	ds_write_b64 v184, v[150:151] offset:35336
	s_waitcnt lgkmcnt(10)
	v_mfma_f32_32x32x16_bf16 v[80:95], v[204:207], v[112:115], 0
	v_exp_f32_e32 v96, v96
	v_exp_f32_e32 v97, v97
	v_exp_f32_e32 v98, v98
	ds_write_b64 v184, v[152:153] offset:39680
	ds_write_b64 v184, v[154:155] offset:39688
	s_waitcnt lgkmcnt(11)
	v_mfma_f32_32x32x16_bf16 v[80:95], v[208:211], v[116:119], v[80:95]
	v_exp_f32_e32 v99, v99
	v_exp_f32_e32 v100, v100
	v_exp_f32_e32 v101, v101
	global_load_dwordx4 v[136:139], v166, s[10:11]
	global_load_dwordx4 v[140:143], v168, s[10:11]
	global_load_dwordx4 v[144:147], v170, s[10:11]
	global_load_dwordx4 v[148:151], v162, s[2:3]
	global_load_dwordx4 v[152:155], v164, s[2:3]
	s_add_u32 s10, s10, 0x3000
	s_addc_u32 s11, s11, 0
	s_add_u32 s2, s2, 0x80
	s_addc_u32 s3, s3, 0
	s_waitcnt lgkmcnt(10)
	v_mfma_f32_32x32x16_bf16 v[80:95], v[212:215], v[120:123], v[80:95]
	v_exp_f32_e32 v102, v102
	v_exp_f32_e32 v103, v103
	v_add_f32_e32 v203, v203, v96
	v_add_f32_e32 v203, v203, v97
	s_waitcnt lgkmcnt(9)
	v_mfma_f32_32x32x16_bf16 v[80:95], v[216:219], v[124:127], v[80:95]
	v_add_f32_e32 v203, v203, v98
	v_add_f32_e32 v203, v203, v99
	v_add_f32_e32 v203, v203, v100
	v_add_f32_e32 v203, v203, v101
	v_add_f32_e32 v203, v203, v102
	v_add_f32_e32 v203, v203, v103
	s_waitcnt lgkmcnt(8)
	v_mfma_f32_32x32x16_bf16 v[80:95], v[220:223], v[128:131], v[80:95]
	v_cvt_pk_bf16_f32 v96, v96, v97
	v_cvt_pk_bf16_f32 v97, v98, v99
	v_cvt_pk_bf16_f32 v98, v100, v101
	v_cvt_pk_bf16_f32 v99, v102, v103
	v_exp_f32_e32 v104, v104
	s_waitcnt lgkmcnt(7)
	v_mfma_f32_32x32x16_bf16 v[80:95], v[224:227], v[132:135], v[80:95]
	v_exp_f32_e32 v105, v105
	v_exp_f32_e32 v106, v106
	v_exp_f32_e32 v107, v107
	s_waitcnt lgkmcnt(0)
	s_barrier
	v_mfma_f32_32x32x16_bf16 v[32:47], v[4:7], v[96:99], v[32:47]
	v_exp_f32_e32 v108, v108
	v_exp_f32_e32 v109, v109
	v_exp_f32_e32 v110, v110
	ds_read_b64 v[4:5], v202 offset:13376
	ds_read_b64 v[6:7], v202 offset:13392
	v_mfma_f32_32x32x16_bf16 v[16:31], v[8:11], v[96:99], v[16:31]
	v_exp_f32_e32 v111, v111
	v_add_f32_e32 v203, v203, v104
	v_add_f32_e32 v203, v203, v105
	v_add_f32_e32 v203, v203, v106
	v_add_f32_e32 v203, v203, v107
	ds_read_b64 v[8:9], v202 offset:17728
	ds_read_b64 v[10:11], v202 offset:17744
	v_add_f32_e32 v203, v203, v108
	v_add_f32_e32 v203, v203, v109
	v_add_f32_e32 v203, v203, v110
	v_add_f32_e32 v203, v203, v111
	v_cvt_pk_bf16_f32 v104, v104, v105
	v_cvt_pk_bf16_f32 v105, v106, v107
	v_cvt_pk_bf16_f32 v106, v108, v109
	v_cvt_pk_bf16_f32 v107, v110, v111
	s_nop 1
	v_mfma_f32_32x32x16_bf16 v[32:47], v[12:15], v[104:107], v[32:47]
	s_cmp_eq_u32 s9, 0
	s_cbranch_scc1 .Lattn_01_A_nosub
	v_sub_f32_e32 v80, v80, v2
	v_sub_f32_e32 v81, v81, v2
	v_sub_f32_e32 v82, v82, v2
	v_sub_f32_e32 v83, v83, v2
	v_sub_f32_e32 v84, v84, v2
	v_sub_f32_e32 v85, v85, v2
	v_sub_f32_e32 v86, v86, v2
	v_sub_f32_e32 v87, v87, v2
	v_sub_f32_e32 v88, v88, v2
	v_sub_f32_e32 v89, v89, v2
	v_sub_f32_e32 v90, v90, v2
	v_sub_f32_e32 v91, v91, v2
	v_sub_f32_e32 v92, v92, v2
	v_sub_f32_e32 v93, v93, v2
	v_sub_f32_e32 v94, v94, v2
	v_sub_f32_e32 v95, v95, v2
.Lattn_01_A_nosub:
	v_max3_f32 v185, v80, v81, v82
	v_max3_f32 v185, v185, v83, v84
	v_max3_f32 v185, v185, v85, v86
	v_max3_f32 v185, v185, v87, v88
	v_max3_f32 v185, v185, v89, v90
	ds_read_b64 v[12:13], v202 offset:13408
	ds_read_b64 v[14:15], v202 offset:13424
	v_mfma_f32_32x32x16_bf16 v[16:31], v[192:195], v[104:107], v[16:31]
	v_max3_f32 v185, v185, v91, v92
	v_max3_f32 v185, v185, v93, v94
	v_max_f32_e32 v185, v185, v95
	v_cmp_lt_f32_e32 vcc, s33, v185
	s_cbranch_vccnz .Lattn_01_A_rare
.Lattn_01_A_back:
	ds_read_b64 v[192:193], v202 offset:17760
	ds_read_b64 v[194:195], v202 offset:17776
	v_mfma_f32_32x32x16_bf16 v[96:111], v[204:207], v[228:231], 0
	v_exp_f32_e32 v80, v80
	v_exp_f32_e32 v81, v81
	v_exp_f32_e32 v82, v82
	ds_read_b128 v[204:207], v159 offset:22016
	v_mfma_f32_32x32x16_bf16 v[96:111], v[208:211], v[232:235], v[96:111]
	v_exp_f32_e32 v83, v83
	v_exp_f32_e32 v84, v84
	v_exp_f32_e32 v85, v85
	ds_read_b128 v[208:211], v159 offset:22048
	v_mfma_f32_32x32x16_bf16 v[96:111], v[212:215], v[236:239], v[96:111]
	v_exp_f32_e32 v86, v86
	v_exp_f32_e32 v87, v87
	v_add_f32_e32 v0, v0, v80
	v_add_f32_e32 v0, v0, v81
	ds_read_b128 v[212:215], v159 offset:22080
	v_mfma_f32_32x32x16_bf16 v[96:111], v[216:219], v[240:243], v[96:111]
	v_add_f32_e32 v0, v0, v82
	v_add_f32_e32 v0, v0, v83
	v_add_f32_e32 v0, v0, v84
	v_add_f32_e32 v0, v0, v85
	v_add_f32_e32 v0, v0, v86
	v_add_f32_e32 v0, v0, v87
	ds_read_b128 v[216:219], v159 offset:22112
	v_mfma_f32_32x32x16_bf16 v[96:111], v[220:223], v[244:247], v[96:111]
	v_cvt_pk_bf16_f32 v80, v80, v81
	v_cvt_pk_bf16_f32 v81, v82, v83
	v_cvt_pk_bf16_f32 v82, v84, v85
	v_cvt_pk_bf16_f32 v83, v86, v87
	v_exp_f32_e32 v88, v88
	ds_read_b128 v[220:223], v159 offset:22144
	v_mfma_f32_32x32x16_bf16 v[96:111], v[224:227], v[248:251], v[96:111]
	v_exp_f32_e32 v89, v89
	v_exp_f32_e32 v90, v90
	v_exp_f32_e32 v91, v91
	ds_read_b128 v[224:227], v159 offset:22176
	s_waitcnt lgkmcnt(12)
	v_mfma_f32_32x32x16_bf16 v[64:79], v[4:7], v[80:83], v[64:79]
	v_exp_f32_e32 v92, v92
	v_exp_f32_e32 v93, v93
	v_exp_f32_e32 v94, v94
	s_waitcnt lgkmcnt(10)
	v_mfma_f32_32x32x16_bf16 v[48:63], v[8:11], v[80:83], v[48:63]
	v_exp_f32_e32 v95, v95
	v_add_f32_e32 v0, v0, v88
	v_add_f32_e32 v0, v0, v89
	v_add_f32_e32 v0, v0, v90
	v_add_f32_e32 v0, v0, v91
	s_waitcnt lgkmcnt(8)
	v_add_f32_e32 v0, v0, v92
	v_add_f32_e32 v0, v0, v93
	v_add_f32_e32 v0, v0, v94
	v_add_f32_e32 v0, v0, v95
	v_cvt_pk_bf16_f32 v88, v88, v89
	v_cvt_pk_bf16_f32 v89, v90, v91
	v_cvt_pk_bf16_f32 v90, v92, v93
	v_cvt_pk_bf16_f32 v91, v94, v95
	s_nop 1
	v_mfma_f32_32x32x16_bf16 v[64:79], v[12:15], v[88:91], v[64:79]
	s_cmp_eq_u32 s12, 0
	s_cbranch_scc1 .Lattn_01_B_nosub
	v_sub_f32_e32 v96, v96, v201
	v_sub_f32_e32 v97, v97, v201
	v_sub_f32_e32 v98, v98, v201
	v_sub_f32_e32 v99, v99, v201
	v_sub_f32_e32 v100, v100, v201
	v_sub_f32_e32 v101, v101, v201
	v_sub_f32_e32 v102, v102, v201
	v_sub_f32_e32 v103, v103, v201
	v_sub_f32_e32 v104, v104, v201
	v_sub_f32_e32 v105, v105, v201
	v_sub_f32_e32 v106, v106, v201
	v_sub_f32_e32 v107, v107, v201
	v_sub_f32_e32 v108, v108, v201
	v_sub_f32_e32 v109, v109, v201
	v_sub_f32_e32 v110, v110, v201
	v_sub_f32_e32 v111, v111, v201
; #define MFMA32(a, b, c) __builtin_amdgcn_mfma_f32_32x32x16_bf16((a), (b), (c), 0, 0, 0)
; DI void attn_item(const Ctx& c, int item, bf16* lds) {
;     ...
;       if (__builtin_amdgcn_ballot_w64(m[qs] != 0.f) != 0ull) {
; #pragma unroll
;         for (int i = 0; i < 16; ++i) { st[0][i] -= m[qs]; st[1][i] -= m[qs]; }
;       }
;       float mx = st[0][0];
; #pragma unroll
;       for (int i = 1; i < 16; ++i) mx = fmaxf(mx, st[0][i]);
; #pragma unroll
;       for (int i = 0; i < 16; ++i) mx = fmaxf(mx, st[1][i]);
;       mx = xhalf_max(mx);
;       if (__builtin_amdgcn_ballot_w64((kt == 0) ? (fabsf(mx) > 16.f) : (mx > 16.f)) != 0ull) {
;         const float d = (kt == 0) ? mx : fmaxf(mx, 0.f);
;         const float alpha = __builtin_amdgcn_exp2f(-d);
;         m[qs] += d; lsum[qs] *= alpha;
; #pragma unroll
;         for (int i = 0; i < 16; ++i) { ot[qs][0][i] *= alpha; ot[qs][1][i] *= alpha; st[0][i] -= d; st[1][i] -= d; }
;       }
;       float ps = 0.f;
; #pragma unroll
;       for (int sp = 0; sp < 4; ++sp) {
;         const int mt = sp >> 1, s2 = sp & 1;
;         float e[8];
; #pragma unroll
;         for (int j = 0; j < 8; ++j) { e[j] = __builtin_amdgcn_exp2f(st[mt][8 * s2 + j]); ps += e[j]; }
;         u32x4 pk;
;         pk[0] = pk2(e[0], e[1]); pk[1] = pk2(e[2], e[3]); pk[2] = pk2(e[4], e[5]); pk[3] = pk2(e[6], e[7]);
;         const bf16x8 pf = __builtin_bit_cast(bf16x8, pk);
; #pragma unroll
;         for (int vt = 0; vt < 2; ++vt) {
;           const bf16* vp = Vs + (32 * vt + r) * AV_LD + 32 * mt + 16 * s2 + 4 * hh;
;           const s16x4 lo = *(const s16x4*)(vp), hi = *(const s16x4*)(vp + 8);
;           const bf16x8 a = __builtin_shufflevector(lo, hi, 0, 1, 2, 3, 4, 5, 6, 7);
;           ot[qs][vt] = MFMA32(a, pf, ot[qs][vt]);
;         }
;       }
;       lsum[qs] += ps;
.Lattn_01_B_nosub:
	v_max3_f32 v185, v96, v97, v98
	v_max3_f32 v185, v185, v99, v100
	v_max3_f32 v185, v185, v101, v102
	v_max3_f32 v185, v185, v103, v104
	v_max3_f32 v185, v185, v105, v106
	s_waitcnt lgkmcnt(6)
	v_mfma_f32_32x32x16_bf16 v[48:63], v[192:195], v[88:91], v[48:63]
	v_max3_f32 v185, v185, v107, v108
	v_max3_f32 v185, v185, v109, v110
	v_max_f32_e32 v185, v185, v111
	v_cmp_lt_f32_e32 vcc, s33, v185
	s_cbranch_vccnz .Lattn_01_B_rare
.Lattn_01_B_back:
	s_waitcnt lgkmcnt(5)
	v_mfma_f32_32x32x16_bf16 v[80:95], v[204:207], v[112:115], 0
	v_exp_f32_e32 v96, v96
	v_exp_f32_e32 v97, v97
	v_exp_f32_e32 v98, v98
	s_waitcnt lgkmcnt(4)
	v_mfma_f32_32x32x16_bf16 v[80:95], v[208:211], v[116:119], v[80:95]
	v_exp_f32_e32 v99, v99
	v_exp_f32_e32 v100, v100
	v_exp_f32_e32 v101, v101
	s_waitcnt lgkmcnt(3)
	v_mfma_f32_32x32x16_bf16 v[80:95], v[212:215], v[120:123], v[80:95]
	v_exp_f32_e32 v102, v102
	v_exp_f32_e32 v103, v103
	v_add_f32_e32 v203, v203, v96
	v_add_f32_e32 v203, v203, v97
	s_waitcnt lgkmcnt(2)
	v_mfma_f32_32x32x16_bf16 v[80:95], v[216:219], v[124:127], v[80:95]
	v_add_f32_e32 v203, v203, v98
	v_add_f32_e32 v203, v203, v99
	v_add_f32_e32 v203, v203, v100
	v_add_f32_e32 v203, v203, v101
	v_add_f32_e32 v203, v203, v102
	v_add_f32_e32 v203, v203, v103
	s_waitcnt lgkmcnt(1)
	v_mfma_f32_32x32x16_bf16 v[80:95], v[220:223], v[128:131], v[80:95]
	v_cvt_pk_bf16_f32 v96, v96, v97
	v_cvt_pk_bf16_f32 v97, v98, v99
	v_cvt_pk_bf16_f32 v98, v100, v101
	v_cvt_pk_bf16_f32 v99, v102, v103
	v_exp_f32_e32 v104, v104
	s_waitcnt lgkmcnt(0)
	v_mfma_f32_32x32x16_bf16 v[80:95], v[224:227], v[132:135], v[80:95]
	v_exp_f32_e32 v105, v105
	v_exp_f32_e32 v106, v106
	v_exp_f32_e32 v107, v107
	s_add_i32 s1, s1, 1
	v_mfma_f32_32x32x16_bf16 v[32:47], v[4:7], v[96:99], v[32:47]
	v_exp_f32_e32 v108, v108
	v_exp_f32_e32 v109, v109
	v_exp_f32_e32 v110, v110
	ds_read_b64 v[4:5], v202 offset:35328
	ds_read_b64 v[6:7], v202 offset:35344
	v_mfma_f32_32x32x16_bf16 v[16:31], v[8:11], v[96:99], v[16:31]
	v_exp_f32_e32 v111, v111
	v_add_f32_e32 v203, v203, v104
	v_add_f32_e32 v203, v203, v105
	v_add_f32_e32 v203, v203, v106
	v_add_f32_e32 v203, v203, v107
	ds_read_b64 v[8:9], v202 offset:39680
	ds_read_b64 v[10:11], v202 offset:39696
	v_add_f32_e32 v203, v203, v108
	v_add_f32_e32 v203, v203, v109
	v_add_f32_e32 v203, v203, v110
	v_add_f32_e32 v203, v203, v111
	v_cvt_pk_bf16_f32 v104, v104, v105
	v_cvt_pk_bf16_f32 v105, v106, v107
	v_cvt_pk_bf16_f32 v106, v108, v109
	v_cvt_pk_bf16_f32 v107, v110, v111
	s_nop 1
	v_mfma_f32_32x32x16_bf16 v[32:47], v[12:15], v[104:107], v[32:47]
	s_cmp_eq_u32 s9, 0
	s_cbranch_scc1 .Lattn_10_A_nosub
	v_sub_f32_e32 v80, v80, v2
	v_sub_f32_e32 v81, v81, v2
	v_sub_f32_e32 v82, v82, v2
	v_sub_f32_e32 v83, v83, v2
	v_sub_f32_e32 v84, v84, v2
	v_sub_f32_e32 v85, v85, v2
	v_sub_f32_e32 v86, v86, v2
	v_sub_f32_e32 v87, v87, v2
	v_sub_f32_e32 v88, v88, v2
	v_sub_f32_e32 v89, v89, v2
	v_sub_f32_e32 v90, v90, v2
	v_sub_f32_e32 v91, v91, v2
	v_sub_f32_e32 v92, v92, v2
	v_sub_f32_e32 v93, v93, v2
	v_sub_f32_e32 v94, v94, v2
	v_sub_f32_e32 v95, v95, v2
.Lattn_10_A_nosub:
	v_max3_f32 v185, v80, v81, v82
	v_max3_f32 v185, v185, v83, v84
	v_max3_f32 v185, v185, v85, v86
	v_max3_f32 v185, v185, v87, v88
	v_max3_f32 v185, v185, v89, v90
	ds_read_b64 v[12:13], v202 offset:35360
	ds_read_b64 v[14:15], v202 offset:35376
	v_mfma_f32_32x32x16_bf16 v[16:31], v[192:195], v[104:107], v[16:31]
	v_max3_f32 v185, v185, v91, v92
	v_max3_f32 v185, v185, v93, v94
	v_max_f32_e32 v185, v185, v95
	v_cmp_lt_f32_e32 vcc, s33, v185
	s_cbranch_vccnz .Lattn_10_A_rare
.Lattn_10_A_back:
	ds_read_b64 v[192:193], v202 offset:39712
	ds_read_b64 v[194:195], v202 offset:39728
	v_mfma_f32_32x32x16_bf16 v[96:111], v[204:207], v[228:231], 0
	v_exp_f32_e32 v80, v80
	v_exp_f32_e32 v81, v81
	v_exp_f32_e32 v82, v82
	ds_read_b128 v[204:207], v159 offset:28672
	v_mfma_f32_32x32x16_bf16 v[96:111], v[208:211], v[232:235], v[96:111]
	v_exp_f32_e32 v83, v83
	v_exp_f32_e32 v84, v84
	v_exp_f32_e32 v85, v85
	ds_read_b128 v[208:211], v159 offset:28704
	v_mfma_f32_32x32x16_bf16 v[96:111], v[212:215], v[236:239], v[96:111]
	v_exp_f32_e32 v86, v86
	v_exp_f32_e32 v87, v87
	v_add_f32_e32 v0, v0, v80
	v_add_f32_e32 v0, v0, v81
	ds_read_b128 v[212:215], v159 offset:28736
	v_mfma_f32_32x32x16_bf16 v[96:111], v[216:219], v[240:243], v[96:111]
	v_add_f32_e32 v0, v0, v82
	v_add_f32_e32 v0, v0, v83
	v_add_f32_e32 v0, v0, v84
	v_add_f32_e32 v0, v0, v85
	v_add_f32_e32 v0, v0, v86
	v_add_f32_e32 v0, v0, v87
	ds_read_b128 v[216:219], v159 offset:28768
	v_mfma_f32_32x32x16_bf16 v[96:111], v[220:223], v[244:247], v[96:111]
	v_cvt_pk_bf16_f32 v80, v80, v81
	v_cvt_pk_bf16_f32 v81, v82, v83
	v_cvt_pk_bf16_f32 v82, v84, v85
	v_cvt_pk_bf16_f32 v83, v86, v87
	v_exp_f32_e32 v88, v88
	ds_read_b128 v[220:223], v159 offset:28800
	v_mfma_f32_32x32x16_bf16 v[96:111], v[224:227], v[248:251], v[96:111]
	v_exp_f32_e32 v89, v89
	v_exp_f32_e32 v90, v90
	v_exp_f32_e32 v91, v91
	ds_read_b128 v[224:227], v159 offset:28832
	s_waitcnt lgkmcnt(12)
	v_mfma_f32_32x32x16_bf16 v[64:79], v[4:7], v[80:83], v[64:79]
	v_exp_f32_e32 v92, v92
	v_exp_f32_e32 v93, v93
	v_exp_f32_e32 v94, v94
	s_waitcnt vmcnt(0)
	ds_write_b128 v3, v[136:139] offset:44032
	s_waitcnt lgkmcnt(11)
	v_mfma_f32_32x32x16_bf16 v[48:63], v[8:11], v[80:83], v[48:63]
	v_exp_f32_e32 v95, v95
	v_add_f32_e32 v0, v0, v88
	v_add_f32_e32 v0, v0, v89
	v_add_f32_e32 v0, v0, v90
	v_add_f32_e32 v0, v0, v91
	ds_write_b128 v161, v[140:143] offset:44032
	s_waitcnt lgkmcnt(10)
	v_add_f32_e32 v0, v0, v92
	v_add_f32_e32 v0, v0, v93
	v_add_f32_e32 v0, v0, v94
	v_add_f32_e32 v0, v0, v95
	v_cvt_pk_bf16_f32 v88, v88, v89
	v_cvt_pk_bf16_f32 v89, v90, v91
	v_cvt_pk_bf16_f32 v90, v92, v93
	v_cvt_pk_bf16_f32 v91, v94, v95
	s_nop 1
	v_mfma_f32_32x32x16_bf16 v[64:79], v[12:15], v[88:91], v[64:79]
	s_cmp_eq_u32 s12, 0
	s_cbranch_scc1 .Lattn_10_B_nosub
	v_sub_f32_e32 v96, v96, v201
	v_sub_f32_e32 v97, v97, v201
	v_sub_f32_e32 v98, v98, v201
	v_sub_f32_e32 v99, v99, v201
	v_sub_f32_e32 v100, v100, v201
	v_sub_f32_e32 v101, v101, v201
	v_sub_f32_e32 v102, v102, v201
	v_sub_f32_e32 v103, v103, v201
	v_sub_f32_e32 v104, v104, v201
	v_sub_f32_e32 v105, v105, v201
	v_sub_f32_e32 v106, v106, v201
	v_sub_f32_e32 v107, v107, v201
	v_sub_f32_e32 v108, v108, v201
	v_sub_f32_e32 v109, v109, v201
	v_sub_f32_e32 v110, v110, v201
	v_sub_f32_e32 v111, v111, v201
; #define MFMA32(a, b, c) __builtin_amdgcn_mfma_f32_32x32x16_bf16((a), (b), (c), 0, 0, 0)
; DI void attn_item(const Ctx& c, int item, bf16* lds) {
;     ...
;       if (__builtin_amdgcn_ballot_w64(m[qs] != 0.f) != 0ull) {
; #pragma unroll
;         for (int i = 0; i < 16; ++i) { st[0][i] -= m[qs]; st[1][i] -= m[qs]; }
;       }
;       float mx = st[0][0];
; #pragma unroll
;       for (int i = 1; i < 16; ++i) mx = fmaxf(mx, st[0][i]);
; #pragma unroll
;       for (int i = 0; i < 16; ++i) mx = fmaxf(mx, st[1][i]);
;       mx = xhalf_max(mx);
;       if (__builtin_amdgcn_ballot_w64((kt == 0) ? (fabsf(mx) > 16.f) : (mx > 16.f)) != 0ull) {
;         const float d = (kt == 0) ? mx : fmaxf(mx, 0.f);
;         const float alpha = __builtin_amdgcn_exp2f(-d);
;         m[qs] += d; lsum[qs] *= alpha;
; #pragma unroll
;         for (int i = 0; i < 16; ++i) { ot[qs][0][i] *= alpha; ot[qs][1][i] *= alpha; st[0][i] -= d; st[1][i] -= d; }
;       }
;       float ps = 0.f;
; #pragma unroll
;       for (int sp = 0; sp < 4; ++sp) {
;         const int mt = sp >> 1, s2 = sp & 1;
;         float e[8];
; #pragma unroll
;         for (int j = 0; j < 8; ++j) { e[j] = __builtin_amdgcn_exp2f(st[mt][8 * s2 + j]); ps += e[j]; }
;         u32x4 pk;
;         pk[0] = pk2(e[0], e[1]); pk[1] = pk2(e[2], e[3]); pk[2] = pk2(e[4], e[5]); pk[3] = pk2(e[6], e[7]);
;         const bf16x8 pf = __builtin_bit_cast(bf16x8, pk);
; #pragma unroll
;         for (int vt = 0; vt < 2; ++vt) {
;           const bf16* vp = Vs + (32 * vt + r) * AV_LD + 32 * mt + 16 * s2 + 4 * hh;
;           const s16x4 lo = *(const s16x4*)(vp), hi = *(const s16x4*)(vp + 8);
;           const bf16x8 a = __builtin_shufflevector(lo, hi, 0, 1, 2, 3, 4, 5, 6, 7);
;           ot[qs][vt] = MFMA32(a, pf, ot[qs][vt]);
;         }
;       }
;       lsum[qs] += ps;
.Lattn_10_B_nosub:
	v_max3_f32 v185, v96, v97, v98
	v_max3_f32 v185, v185, v99, v100
	v_max3_f32 v185, v185, v101, v102
	v_max3_f32 v185, v185, v103, v104
	v_max3_f32 v185, v185, v105, v106
	ds_write_b128 v182, v[144:147] offset:44032
	s_waitcnt lgkmcnt(9)
	v_mfma_f32_32x32x16_bf16 v[48:63], v[192:195], v[88:91], v[48:63]
	v_max3_f32 v185, v185, v107, v108
	v_max3_f32 v185, v185, v109, v110
	v_max_f32_e32 v185, v185, v111
	v_cmp_lt_f32_e32 vcc, s33, v185
	s_cbranch_vccnz .Lattn_10_B_rare
.Lattn_10_B_back:
	ds_write_b64 v184, v[148:149] offset:57344
	ds_write_b64 v184, v[150:151] offset:57352
	s_waitcnt lgkmcnt(10)
	v_mfma_f32_32x32x16_bf16 v[80:95], v[204:207], v[112:115], 0
	v_exp_f32_e32 v96, v96
	v_exp_f32_e32 v97, v97
	v_exp_f32_e32 v98, v98
	ds_write_b64 v184, v[152:153] offset:61696
	ds_write_b64 v184, v[154:155] offset:61704
	s_waitcnt lgkmcnt(11)
	v_mfma_f32_32x32x16_bf16 v[80:95], v[208:211], v[116:119], v[80:95]
	v_exp_f32_e32 v99, v99
	v_exp_f32_e32 v100, v100
	v_exp_f32_e32 v101, v101
	global_load_dwordx4 v[136:139], v166, s[10:11]
	global_load_dwordx4 v[140:143], v168, s[10:11]
	global_load_dwordx4 v[144:147], v170, s[10:11]
	global_load_dwordx4 v[148:151], v162, s[2:3]
	global_load_dwordx4 v[152:155], v164, s[2:3]
	s_add_u32 s10, s10, 0x3000
	s_addc_u32 s11, s11, 0
	s_add_u32 s2, s2, 0x80
	s_addc_u32 s3, s3, 0
	s_waitcnt lgkmcnt(10)
	v_mfma_f32_32x32x16_bf16 v[80:95], v[212:215], v[120:123], v[80:95]
	v_exp_f32_e32 v102, v102
	v_exp_f32_e32 v103, v103
	v_add_f32_e32 v203, v203, v96
	v_add_f32_e32 v203, v203, v97
	s_waitcnt lgkmcnt(9)
	v_mfma_f32_32x32x16_bf16 v[80:95], v[216:219], v[124:127], v[80:95]
	v_add_f32_e32 v203, v203, v98
	v_add_f32_e32 v203, v203, v99
	v_add_f32_e32 v203, v203, v100
	v_add_f32_e32 v203, v203, v101
	v_add_f32_e32 v203, v203, v102
	v_add_f32_e32 v203, v203, v103
	s_waitcnt lgkmcnt(8)
	v_mfma_f32_32x32x16_bf16 v[80:95], v[220:223], v[128:131], v[80:95]
	v_cvt_pk_bf16_f32 v96, v96, v97
	v_cvt_pk_bf16_f32 v97, v98, v99
	v_cvt_pk_bf16_f32 v98, v100, v101
	v_cvt_pk_bf16_f32 v99, v102, v103
	v_exp_f32_e32 v104, v104
	s_waitcnt lgkmcnt(7)
	v_mfma_f32_32x32x16_bf16 v[80:95], v[224:227], v[132:135], v[80:95]
	v_exp_f32_e32 v105, v105
	v_exp_f32_e32 v106, v106
	v_exp_f32_e32 v107, v107
	s_waitcnt lgkmcnt(0)
	s_barrier
	v_mfma_f32_32x32x16_bf16 v[32:47], v[4:7], v[96:99], v[32:47]
	v_exp_f32_e32 v108, v108
	v_exp_f32_e32 v109, v109
	v_exp_f32_e32 v110, v110
	ds_read_b64 v[4:5], v202 offset:35392
	ds_read_b64 v[6:7], v202 offset:35408
	v_mfma_f32_32x32x16_bf16 v[16:31], v[8:11], v[96:99], v[16:31]
	v_exp_f32_e32 v111, v111
	v_add_f32_e32 v203, v203, v104
	v_add_f32_e32 v203, v203, v105
	v_add_f32_e32 v203, v203, v106
	v_add_f32_e32 v203, v203, v107
	ds_read_b64 v[8:9], v202 offset:39744
	ds_read_b64 v[10:11], v202 offset:39760
	v_add_f32_e32 v203, v203, v108
	v_add_f32_e32 v203, v203, v109
	v_add_f32_e32 v203, v203, v110
	v_add_f32_e32 v203, v203, v111
	v_cvt_pk_bf16_f32 v104, v104, v105
	v_cvt_pk_bf16_f32 v105, v106, v107
	v_cvt_pk_bf16_f32 v106, v108, v109
	v_cvt_pk_bf16_f32 v107, v110, v111
	s_nop 1
	v_mfma_f32_32x32x16_bf16 v[32:47], v[12:15], v[104:107], v[32:47]
	s_cmp_eq_u32 s9, 0
	s_cbranch_scc1 .Lattn_11_A_nosub
	v_sub_f32_e32 v80, v80, v2
	v_sub_f32_e32 v81, v81, v2
	v_sub_f32_e32 v82, v82, v2
	v_sub_f32_e32 v83, v83, v2
	v_sub_f32_e32 v84, v84, v2
	v_sub_f32_e32 v85, v85, v2
	v_sub_f32_e32 v86, v86, v2
	v_sub_f32_e32 v87, v87, v2
	v_sub_f32_e32 v88, v88, v2
	v_sub_f32_e32 v89, v89, v2
	v_sub_f32_e32 v90, v90, v2
	v_sub_f32_e32 v91, v91, v2
	v_sub_f32_e32 v92, v92, v2
	v_sub_f32_e32 v93, v93, v2
	v_sub_f32_e32 v94, v94, v2
	v_sub_f32_e32 v95, v95, v2
.Lattn_11_A_nosub:
	v_max3_f32 v185, v80, v81, v82
	v_max3_f32 v185, v185, v83, v84
	v_max3_f32 v185, v185, v85, v86
	v_max3_f32 v185, v185, v87, v88
	v_max3_f32 v185, v185, v89, v90
	ds_read_b64 v[12:13], v202 offset:35424
	ds_read_b64 v[14:15], v202 offset:35440
	v_mfma_f32_32x32x16_bf16 v[16:31], v[192:195], v[104:107], v[16:31]
	v_max3_f32 v185, v185, v91, v92
	v_max3_f32 v185, v185, v93, v94
	v_max_f32_e32 v185, v185, v95
	v_cmp_lt_f32_e32 vcc, s33, v185
	s_cbranch_vccnz .Lattn_11_A_rare
.Lattn_11_A_back:
	ds_read_b64 v[192:193], v202 offset:39776
	ds_read_b64 v[194:195], v202 offset:39792
	v_mfma_f32_32x32x16_bf16 v[96:111], v[204:207], v[228:231], 0
	v_exp_f32_e32 v80, v80
	v_exp_f32_e32 v81, v81
	v_exp_f32_e32 v82, v82
	ds_read_b128 v[204:207], v159 offset:44032
	v_mfma_f32_32x32x16_bf16 v[96:111], v[208:211], v[232:235], v[96:111]
	v_exp_f32_e32 v83, v83
	v_exp_f32_e32 v84, v84
	v_exp_f32_e32 v85, v85
	ds_read_b128 v[208:211], v159 offset:44064
	v_mfma_f32_32x32x16_bf16 v[96:111], v[212:215], v[236:239], v[96:111]
	v_exp_f32_e32 v86, v86
	v_exp_f32_e32 v87, v87
	v_add_f32_e32 v0, v0, v80
	v_add_f32_e32 v0, v0, v81
	ds_read_b128 v[212:215], v159 offset:44096
	v_mfma_f32_32x32x16_bf16 v[96:111], v[216:219], v[240:243], v[96:111]
	v_add_f32_e32 v0, v0, v82
	v_add_f32_e32 v0, v0, v83
	v_add_f32_e32 v0, v0, v84
	v_add_f32_e32 v0, v0, v85
	v_add_f32_e32 v0, v0, v86
	v_add_f32_e32 v0, v0, v87
	ds_read_b128 v[216:219], v159 offset:44128
	v_mfma_f32_32x32x16_bf16 v[96:111], v[220:223], v[244:247], v[96:111]
	v_cvt_pk_bf16_f32 v80, v80, v81
	v_cvt_pk_bf16_f32 v81, v82, v83
	v_cvt_pk_bf16_f32 v82, v84, v85
	v_cvt_pk_bf16_f32 v83, v86, v87
	v_exp_f32_e32 v88, v88
	ds_read_b128 v[220:223], v159 offset:44160
	v_mfma_f32_32x32x16_bf16 v[96:111], v[224:227], v[248:251], v[96:111]
	v_exp_f32_e32 v89, v89
	v_exp_f32_e32 v90, v90
	v_exp_f32_e32 v91, v91
	ds_read_b128 v[224:227], v159 offset:44192
	s_waitcnt lgkmcnt(12)
	v_mfma_f32_32x32x16_bf16 v[64:79], v[4:7], v[80:83], v[64:79]
	v_exp_f32_e32 v92, v92
	v_exp_f32_e32 v93, v93
	v_exp_f32_e32 v94, v94
	s_waitcnt lgkmcnt(10)
	v_mfma_f32_32x32x16_bf16 v[48:63], v[8:11], v[80:83], v[48:63]
	v_exp_f32_e32 v95, v95
	v_add_f32_e32 v0, v0, v88
	v_add_f32_e32 v0, v0, v89
	v_add_f32_e32 v0, v0, v90
	v_add_f32_e32 v0, v0, v91
	s_waitcnt lgkmcnt(8)
	v_add_f32_e32 v0, v0, v92
	v_add_f32_e32 v0, v0, v93
	v_add_f32_e32 v0, v0, v94
	v_add_f32_e32 v0, v0, v95
	v_cvt_pk_bf16_f32 v88, v88, v89
	v_cvt_pk_bf16_f32 v89, v90, v91
	v_cvt_pk_bf16_f32 v90, v92, v93
	v_cvt_pk_bf16_f32 v91, v94, v95
	s_nop 1
	v_mfma_f32_32x32x16_bf16 v[64:79], v[12:15], v[88:91], v[64:79]
	s_cmp_eq_u32 s12, 0
	s_cbranch_scc1 .Lattn_11_B_nosub
	v_sub_f32_e32 v96, v96, v201
	v_sub_f32_e32 v97, v97, v201
	v_sub_f32_e32 v98, v98, v201
	v_sub_f32_e32 v99, v99, v201
	v_sub_f32_e32 v100, v100, v201
	v_sub_f32_e32 v101, v101, v201
	v_sub_f32_e32 v102, v102, v201
	v_sub_f32_e32 v103, v103, v201
	v_sub_f32_e32 v104, v104, v201
	v_sub_f32_e32 v105, v105, v201
	v_sub_f32_e32 v106, v106, v201
	v_sub_f32_e32 v107, v107, v201
	v_sub_f32_e32 v108, v108, v201
	v_sub_f32_e32 v109, v109, v201
	v_sub_f32_e32 v110, v110, v201
	v_sub_f32_e32 v111, v111, v201

; #define MFMA32(a, b, c) __builtin_amdgcn_mfma_f32_32x32x16_bf16((a), (b), (c), 0, 0, 0)
; DI void attn_item(const Ctx& c, int item, bf16* lds) {
;     ...
;       if (__builtin_amdgcn_ballot_w64(m[qs] != 0.f) != 0ull) {
; #pragma unroll
;         for (int i = 0; i < 16; ++i) { st[0][i] -= m[qs]; st[1][i] -= m[qs]; }
;       }
;       float mx = st[0][0];
; #pragma unroll
;       for (int i = 1; i < 16; ++i) mx = fmaxf(mx, st[0][i]);
; #pragma unroll
;       for (int i = 0; i < 16; ++i) mx = fmaxf(mx, st[1][i]);
;       mx = xhalf_max(mx);
;       if (__builtin_amdgcn_ballot_w64((kt == 0) ? (fabsf(mx) > 16.f) : (mx > 16.f)) != 0ull) {
;         const float d = (kt == 0) ? mx : fmaxf(mx, 0.f);
;         const float alpha = __builtin_amdgcn_exp2f(-d);
;         m[qs] += d; lsum[qs] *= alpha;
; #pragma unroll
;         for (int i = 0; i < 16; ++i) { ot[qs][0][i] *= alpha; ot[qs][1][i] *= alpha; st[0][i] -= d; st[1][i] -= d; }
;       }
;       float ps = 0.f;
; #pragma unroll
;       for (int sp = 0; sp < 4; ++sp) {
;         const int mt = sp >> 1, s2 = sp & 1;
;         float e[8];
; #pragma unroll
;         for (int j = 0; j < 8; ++j) { e[j] = __builtin_amdgcn_exp2f(st[mt][8 * s2 + j]); ps += e[j]; }
;         u32x4 pk;
;         pk[0] = pk2(e[0], e[1]); pk[1] = pk2(e[2], e[3]); pk[2] = pk2(e[4], e[5]); pk[3] = pk2(e[6], e[7]);
;         const bf16x8 pf = __builtin_bit_cast(bf16x8, pk);
; #pragma unroll
;         for (int vt = 0; vt < 2; ++vt) {
;           const bf16* vp = Vs + (32 * vt + r) * AV_LD + 32 * mt + 16 * s2 + 4 * hh;
;           const s16x4 lo = *(const s16x4*)(vp), hi = *(const s16x4*)(vp + 8);
;           const bf16x8 a = __builtin_shufflevector(lo, hi, 0, 1, 2, 3, 4, 5, 6, 7);
;           ot[qs][vt] = MFMA32(a, pf, ot[qs][vt]);
;         }
;       }
;       lsum[qs] += ps;
.Lattn_11_B_back:
	s_waitcnt lgkmcnt(5)
	v_mfma_f32_32x32x16_bf16 v[80:95], v[204:207], v[112:115], 0
	v_exp_f32_e32 v96, v96
	v_exp_f32_e32 v97, v97
	v_exp_f32_e32 v98, v98
	s_waitcnt lgkmcnt(4)
	v_mfma_f32_32x32x16_bf16 v[80:95], v[208:211], v[116:119], v[80:95]
	v_exp_f32_e32 v99, v99
	v_exp_f32_e32 v100, v100
	v_exp_f32_e32 v101, v101
	s_waitcnt lgkmcnt(3)
	v_mfma_f32_32x32x16_bf16 v[80:95], v[212:215], v[120:123], v[80:95]
	v_exp_f32_e32 v102, v102
	v_exp_f32_e32 v103, v103
	v_add_f32_e32 v203, v203, v96
	v_add_f32_e32 v203, v203, v97
	s_waitcnt lgkmcnt(2)
	v_mfma_f32_32x32x16_bf16 v[80:95], v[216:219], v[124:127], v[80:95]
	v_add_f32_e32 v203, v203, v98
	v_add_f32_e32 v203, v203, v99
	v_add_f32_e32 v203, v203, v100
	v_add_f32_e32 v203, v203, v101
	v_add_f32_e32 v203, v203, v102
	v_add_f32_e32 v203, v203, v103
	s_waitcnt lgkmcnt(1)
	v_mfma_f32_32x32x16_bf16 v[80:95], v[220:223], v[128:131], v[80:95]
	v_cvt_pk_bf16_f32 v96, v96, v97
	v_cvt_pk_bf16_f32 v97, v98, v99
	v_cvt_pk_bf16_f32 v98, v100, v101
	v_cvt_pk_bf16_f32 v99, v102, v103
	v_exp_f32_e32 v104, v104
	s_waitcnt lgkmcnt(0)
	v_mfma_f32_32x32x16_bf16 v[80:95], v[224:227], v[132:135], v[80:95]
	v_exp_f32_e32 v105, v105
	v_exp_f32_e32 v106, v106
	v_exp_f32_e32 v107, v107
	s_add_i32 s1, s1, 1
	v_mfma_f32_32x32x16_bf16 v[32:47], v[4:7], v[96:99], v[32:47]
	v_exp_f32_e32 v108, v108
	v_exp_f32_e32 v109, v109
	v_exp_f32_e32 v110, v110
	ds_read_b64 v[4:5], v202 offset:57344
	ds_read_b64 v[6:7], v202 offset:57360
	v_mfma_f32_32x32x16_bf16 v[16:31], v[8:11], v[96:99], v[16:31]
	v_exp_f32_e32 v111, v111
	v_add_f32_e32 v203, v203, v104
	v_add_f32_e32 v203, v203, v105
	v_add_f32_e32 v203, v203, v106
	v_add_f32_e32 v203, v203, v107
	ds_read_b64 v[8:9], v202 offset:61696
	ds_read_b64 v[10:11], v202 offset:61712
	v_add_f32_e32 v203, v203, v108
	v_add_f32_e32 v203, v203, v109
	v_add_f32_e32 v203, v203, v110
	v_add_f32_e32 v203, v203, v111
	v_cvt_pk_bf16_f32 v104, v104, v105
	v_cvt_pk_bf16_f32 v105, v106, v107
	v_cvt_pk_bf16_f32 v106, v108, v109
	v_cvt_pk_bf16_f32 v107, v110, v111
	s_nop 1
	v_mfma_f32_32x32x16_bf16 v[32:47], v[12:15], v[104:107], v[32:47]
	s_cmp_eq_u32 s9, 0
	s_cbranch_scc1 .Lattn_20_A_nosub
	v_sub_f32_e32 v80, v80, v2
	v_sub_f32_e32 v81, v81, v2
	v_sub_f32_e32 v82, v82, v2
	v_sub_f32_e32 v83, v83, v2
	v_sub_f32_e32 v84, v84, v2
	v_sub_f32_e32 v85, v85, v2
	v_sub_f32_e32 v86, v86, v2
	v_sub_f32_e32 v87, v87, v2
	v_sub_f32_e32 v88, v88, v2
	v_sub_f32_e32 v89, v89, v2
	v_sub_f32_e32 v90, v90, v2
	v_sub_f32_e32 v91, v91, v2
	v_sub_f32_e32 v92, v92, v2
	v_sub_f32_e32 v93, v93, v2
	v_sub_f32_e32 v94, v94, v2
	v_sub_f32_e32 v95, v95, v2
.Lattn_20_A_nosub:
	v_max3_f32 v185, v80, v81, v82
	v_max3_f32 v185, v185, v83, v84
	v_max3_f32 v185, v185, v85, v86
	v_max3_f32 v185, v185, v87, v88
	v_max3_f32 v185, v185, v89, v90
	ds_read_b64 v[12:13], v202 offset:57376
	ds_read_b64 v[14:15], v202 offset:57392
	v_mfma_f32_32x32x16_bf16 v[16:31], v[192:195], v[104:107], v[16:31]
	v_max3_f32 v185, v185, v91, v92
	v_max3_f32 v185, v185, v93, v94
	v_max_f32_e32 v185, v185, v95
	v_cmp_lt_f32_e32 vcc, s33, v185
	s_cbranch_vccnz .Lattn_20_A_rare
.Lattn_20_A_back:
	ds_read_b64 v[192:193], v202 offset:61728
	ds_read_b64 v[194:195], v202 offset:61744
	v_mfma_f32_32x32x16_bf16 v[96:111], v[204:207], v[228:231], 0
	v_exp_f32_e32 v80, v80
	v_exp_f32_e32 v81, v81
	v_exp_f32_e32 v82, v82
	ds_read_b128 v[204:207], v159 offset:50688
	v_mfma_f32_32x32x16_bf16 v[96:111], v[208:211], v[232:235], v[96:111]
	v_exp_f32_e32 v83, v83
	v_exp_f32_e32 v84, v84
	v_exp_f32_e32 v85, v85
	ds_read_b128 v[208:211], v159 offset:50720
	v_mfma_f32_32x32x16_bf16 v[96:111], v[212:215], v[236:239], v[96:111]
	v_exp_f32_e32 v86, v86
	v_exp_f32_e32 v87, v87
	v_add_f32_e32 v0, v0, v80
	v_add_f32_e32 v0, v0, v81
	ds_read_b128 v[212:215], v159 offset:50752
	v_mfma_f32_32x32x16_bf16 v[96:111], v[216:219], v[240:243], v[96:111]
	v_add_f32_e32 v0, v0, v82
	v_add_f32_e32 v0, v0, v83
	v_add_f32_e32 v0, v0, v84
	v_add_f32_e32 v0, v0, v85
	v_add_f32_e32 v0, v0, v86
	v_add_f32_e32 v0, v0, v87
	ds_read_b128 v[216:219], v159 offset:50784
	v_mfma_f32_32x32x16_bf16 v[96:111], v[220:223], v[244:247], v[96:111]
	v_cvt_pk_bf16_f32 v80, v80, v81
	v_cvt_pk_bf16_f32 v81, v82, v83
	v_cvt_pk_bf16_f32 v82, v84, v85
	v_cvt_pk_bf16_f32 v83, v86, v87
	v_exp_f32_e32 v88, v88
	ds_read_b128 v[220:223], v159 offset:50816
	v_mfma_f32_32x32x16_bf16 v[96:111], v[224:227], v[248:251], v[96:111]
	v_exp_f32_e32 v89, v89
	v_exp_f32_e32 v90, v90
	v_exp_f32_e32 v91, v91
	ds_read_b128 v[224:227], v159 offset:50848
	s_waitcnt lgkmcnt(12)
	v_mfma_f32_32x32x16_bf16 v[64:79], v[4:7], v[80:83], v[64:79]
	v_exp_f32_e32 v92, v92
	v_exp_f32_e32 v93, v93
	v_exp_f32_e32 v94, v94
	s_waitcnt vmcnt(0)
	ds_write_b128 v3, v[136:139] offset:0
	s_waitcnt lgkmcnt(11)
	v_mfma_f32_32x32x16_bf16 v[48:63], v[8:11], v[80:83], v[48:63]
	v_exp_f32_e32 v95, v95
	v_add_f32_e32 v0, v0, v88
	v_add_f32_e32 v0, v0, v89
	v_add_f32_e32 v0, v0, v90
	v_add_f32_e32 v0, v0, v91
	ds_write_b128 v161, v[140:143] offset:0
	s_waitcnt lgkmcnt(10)
	v_add_f32_e32 v0, v0, v92
	v_add_f32_e32 v0, v0, v93
	v_add_f32_e32 v0, v0, v94
	v_add_f32_e32 v0, v0, v95
	v_cvt_pk_bf16_f32 v88, v88, v89
	v_cvt_pk_bf16_f32 v89, v90, v91
	v_cvt_pk_bf16_f32 v90, v92, v93
	v_cvt_pk_bf16_f32 v91, v94, v95
	s_nop 1
	v_mfma_f32_32x32x16_bf16 v[64:79], v[12:15], v[88:91], v[64:79]
	s_cmp_eq_u32 s12, 0
	s_cbranch_scc1 .Lattn_20_B_nosub
	v_sub_f32_e32 v96, v96, v201
	v_sub_f32_e32 v97, v97, v201
	v_sub_f32_e32 v98, v98, v201
	v_sub_f32_e32 v99, v99, v201
	v_sub_f32_e32 v100, v100, v201
	v_sub_f32_e32 v101, v101, v201
	v_sub_f32_e32 v102, v102, v201
	v_sub_f32_e32 v103, v103, v201
	v_sub_f32_e32 v104, v104, v201
	v_sub_f32_e32 v105, v105, v201
	v_sub_f32_e32 v106, v106, v201
	v_sub_f32_e32 v107, v107, v201
	v_sub_f32_e32 v108, v108, v201
	v_sub_f32_e32 v109, v109, v201
	v_sub_f32_e32 v110, v110, v201
	v_sub_f32_e32 v111, v111, v201
; #define MFMA32(a, b, c) __builtin_amdgcn_mfma_f32_32x32x16_bf16((a), (b), (c), 0, 0, 0)
; DI void attn_item(const Ctx& c, int item, bf16* lds) {
;     ...
;       if (__builtin_amdgcn_ballot_w64(m[qs] != 0.f) != 0ull) {
; #pragma unroll
;         for (int i = 0; i < 16; ++i) { st[0][i] -= m[qs]; st[1][i] -= m[qs]; }
;       }
;       float mx = st[0][0];
; #pragma unroll
;       for (int i = 1; i < 16; ++i) mx = fmaxf(mx, st[0][i]);
; #pragma unroll
;       for (int i = 0; i < 16; ++i) mx = fmaxf(mx, st[1][i]);
;       mx = xhalf_max(mx);
;       if (__builtin_amdgcn_ballot_w64((kt == 0) ? (fabsf(mx) > 16.f) : (mx > 16.f)) != 0ull) {
;         const float d = (kt == 0) ? mx : fmaxf(mx, 0.f);
;         const float alpha = __builtin_amdgcn_exp2f(-d);
;         m[qs] += d; lsum[qs] *= alpha;
; #pragma unroll
;         for (int i = 0; i < 16; ++i) { ot[qs][0][i] *= alpha; ot[qs][1][i] *= alpha; st[0][i] -= d; st[1][i] -= d; }
;       }
;       float ps = 0.f;
; #pragma unroll
;       for (int sp = 0; sp < 4; ++sp) {
;         const int mt = sp >> 1, s2 = sp & 1;
;         float e[8];
; #pragma unroll
;         for (int j = 0; j < 8; ++j) { e[j] = __builtin_amdgcn_exp2f(st[mt][8 * s2 + j]); ps += e[j]; }
;         u32x4 pk;
;         pk[0] = pk2(e[0], e[1]); pk[1] = pk2(e[2], e[3]); pk[2] = pk2(e[4], e[5]); pk[3] = pk2(e[6], e[7]);
;         const bf16x8 pf = __builtin_bit_cast(bf16x8, pk);
; #pragma unroll
;         for (int vt = 0; vt < 2; ++vt) {
;           const bf16* vp = Vs + (32 * vt + r) * AV_LD + 32 * mt + 16 * s2 + 4 * hh;
;           const s16x4 lo = *(const s16x4*)(vp), hi = *(const s16x4*)(vp + 8);
;           const bf16x8 a = __builtin_shufflevector(lo, hi, 0, 1, 2, 3, 4, 5, 6, 7);
;           ot[qs][vt] = MFMA32(a, pf, ot[qs][vt]);
;         }
;       }
;       lsum[qs] += ps;
.Lattn_20_B_nosub:
	v_max3_f32 v185, v96, v97, v98
	v_max3_f32 v185, v185, v99, v100
	v_max3_f32 v185, v185, v101, v102
	v_max3_f32 v185, v185, v103, v104
	v_max3_f32 v185, v185, v105, v106
	ds_write_b128 v182, v[144:147] offset:0
	s_waitcnt lgkmcnt(9)
	v_mfma_f32_32x32x16_bf16 v[48:63], v[192:195], v[88:91], v[48:63]
	v_max3_f32 v185, v185, v107, v108
	v_max3_f32 v185, v185, v109, v110
	v_max_f32_e32 v185, v185, v111
	v_cmp_lt_f32_e32 vcc, s33, v185
	s_cbranch_vccnz .Lattn_20_B_rare
.Lattn_20_B_back:
	ds_write_b64 v184, v[148:149] offset:13312
	ds_write_b64 v184, v[150:151] offset:13320
	s_waitcnt lgkmcnt(10)
	v_mfma_f32_32x32x16_bf16 v[80:95], v[204:207], v[112:115], 0
	v_exp_f32_e32 v96, v96
	v_exp_f32_e32 v97, v97
	v_exp_f32_e32 v98, v98
	ds_write_b64 v184, v[152:153] offset:17664
	ds_write_b64 v184, v[154:155] offset:17672
	s_waitcnt lgkmcnt(11)
	v_mfma_f32_32x32x16_bf16 v[80:95], v[208:211], v[116:119], v[80:95]
	v_exp_f32_e32 v99, v99
	v_exp_f32_e32 v100, v100
	v_exp_f32_e32 v101, v101
	global_load_dwordx4 v[136:139], v166, s[10:11]
	global_load_dwordx4 v[140:143], v168, s[10:11]
	global_load_dwordx4 v[144:147], v170, s[10:11]
	global_load_dwordx4 v[148:151], v162, s[2:3]
	global_load_dwordx4 v[152:155], v164, s[2:3]
	s_add_u32 s10, s10, 0x3000
	s_addc_u32 s11, s11, 0
	s_add_u32 s2, s2, 0x80
	s_addc_u32 s3, s3, 0
	s_waitcnt lgkmcnt(10)
	v_mfma_f32_32x32x16_bf16 v[80:95], v[212:215], v[120:123], v[80:95]
	v_exp_f32_e32 v102, v102
	v_exp_f32_e32 v103, v103
	v_add_f32_e32 v203, v203, v96
	v_add_f32_e32 v203, v203, v97
	s_waitcnt lgkmcnt(9)
	v_mfma_f32_32x32x16_bf16 v[80:95], v[216:219], v[124:127], v[80:95]
	v_add_f32_e32 v203, v203, v98
	v_add_f32_e32 v203, v203, v99
	v_add_f32_e32 v203, v203, v100
	v_add_f32_e32 v203, v203, v101
	v_add_f32_e32 v203, v203, v102
	v_add_f32_e32 v203, v203, v103
	s_waitcnt lgkmcnt(8)
	v_mfma_f32_32x32x16_bf16 v[80:95], v[220:223], v[128:131], v[80:95]
	v_cvt_pk_bf16_f32 v96, v96, v97
	v_cvt_pk_bf16_f32 v97, v98, v99
	v_cvt_pk_bf16_f32 v98, v100, v101
	v_cvt_pk_bf16_f32 v99, v102, v103
	v_exp_f32_e32 v104, v104
	s_waitcnt lgkmcnt(7)
	v_mfma_f32_32x32x16_bf16 v[80:95], v[224:227], v[132:135], v[80:95]
	v_exp_f32_e32 v105, v105
	v_exp_f32_e32 v106, v106
	v_exp_f32_e32 v107, v107
	s_waitcnt lgkmcnt(0)
	s_barrier
	v_mfma_f32_32x32x16_bf16 v[32:47], v[4:7], v[96:99], v[32:47]
	v_exp_f32_e32 v108, v108
	v_exp_f32_e32 v109, v109
	v_exp_f32_e32 v110, v110
	ds_read_b64 v[4:5], v202 offset:57408
	ds_read_b64 v[6:7], v202 offset:57424
	v_mfma_f32_32x32x16_bf16 v[16:31], v[8:11], v[96:99], v[16:31]
	v_exp_f32_e32 v111, v111
	v_add_f32_e32 v203, v203, v104
	v_add_f32_e32 v203, v203, v105
	v_add_f32_e32 v203, v203, v106
	v_add_f32_e32 v203, v203, v107
	ds_read_b64 v[8:9], v202 offset:61760
	ds_read_b64 v[10:11], v202 offset:61776
	v_add_f32_e32 v203, v203, v108
	v_add_f32_e32 v203, v203, v109
	v_add_f32_e32 v203, v203, v110
	v_add_f32_e32 v203, v203, v111
	v_cvt_pk_bf16_f32 v104, v104, v105
	v_cvt_pk_bf16_f32 v105, v106, v107
	v_cvt_pk_bf16_f32 v106, v108, v109
	v_cvt_pk_bf16_f32 v107, v110, v111
	s_nop 1
	v_mfma_f32_32x32x16_bf16 v[32:47], v[12:15], v[104:107], v[32:47]
	s_cmp_eq_u32 s9, 0
	s_cbranch_scc1 .Lattn_21_A_nosub
	v_sub_f32_e32 v80, v80, v2
	v_sub_f32_e32 v81, v81, v2
	v_sub_f32_e32 v82, v82, v2
	v_sub_f32_e32 v83, v83, v2
	v_sub_f32_e32 v84, v84, v2
	v_sub_f32_e32 v85, v85, v2
	v_sub_f32_e32 v86, v86, v2
	v_sub_f32_e32 v87, v87, v2
	v_sub_f32_e32 v88, v88, v2
	v_sub_f32_e32 v89, v89, v2
	v_sub_f32_e32 v90, v90, v2
	v_sub_f32_e32 v91, v91, v2
	v_sub_f32_e32 v92, v92, v2
	v_sub_f32_e32 v93, v93, v2
	v_sub_f32_e32 v94, v94, v2
	v_sub_f32_e32 v95, v95, v2
.Lattn_21_A_nosub:
	v_max3_f32 v185, v80, v81, v82
	v_max3_f32 v185, v185, v83, v84
	v_max3_f32 v185, v185, v85, v86
	v_max3_f32 v185, v185, v87, v88
	v_max3_f32 v185, v185, v89, v90
	ds_read_b64 v[12:13], v202 offset:57440
	ds_read_b64 v[14:15], v202 offset:57456
	v_mfma_f32_32x32x16_bf16 v[16:31], v[192:195], v[104:107], v[16:31]
	v_max3_f32 v185, v185, v91, v92
	v_max3_f32 v185, v185, v93, v94
	v_max_f32_e32 v185, v185, v95
	v_cmp_lt_f32_e32 vcc, s33, v185
	s_cbranch_vccnz .Lattn_21_A_rare
.Lattn_21_A_back:
	ds_read_b64 v[192:193], v202 offset:61792
	ds_read_b64 v[194:195], v202 offset:61808
	v_mfma_f32_32x32x16_bf16 v[96:111], v[204:207], v[228:231], 0
	v_exp_f32_e32 v80, v80
	v_exp_f32_e32 v81, v81
	v_exp_f32_e32 v82, v82
	ds_read_b128 v[204:207], v159 offset:0
	v_mfma_f32_32x32x16_bf16 v[96:111], v[208:211], v[232:235], v[96:111]
	v_exp_f32_e32 v83, v83
	v_exp_f32_e32 v84, v84
	v_exp_f32_e32 v85, v85
	ds_read_b128 v[208:211], v159 offset:32
	v_mfma_f32_32x32x16_bf16 v[96:111], v[212:215], v[236:239], v[96:111]
	v_exp_f32_e32 v86, v86
	v_exp_f32_e32 v87, v87
	v_add_f32_e32 v0, v0, v80
	v_add_f32_e32 v0, v0, v81
	ds_read_b128 v[212:215], v159 offset:64
	v_mfma_f32_32x32x16_bf16 v[96:111], v[216:219], v[240:243], v[96:111]
	v_add_f32_e32 v0, v0, v82
	v_add_f32_e32 v0, v0, v83
	v_add_f32_e32 v0, v0, v84
	v_add_f32_e32 v0, v0, v85
	v_add_f32_e32 v0, v0, v86
	v_add_f32_e32 v0, v0, v87
	ds_read_b128 v[216:219], v159 offset:96
	v_mfma_f32_32x32x16_bf16 v[96:111], v[220:223], v[244:247], v[96:111]
	v_cvt_pk_bf16_f32 v80, v80, v81
	v_cvt_pk_bf16_f32 v81, v82, v83
	v_cvt_pk_bf16_f32 v82, v84, v85
	v_cvt_pk_bf16_f32 v83, v86, v87
	v_exp_f32_e32 v88, v88
	ds_read_b128 v[220:223], v159 offset:128
	v_mfma_f32_32x32x16_bf16 v[96:111], v[224:227], v[248:251], v[96:111]
	v_exp_f32_e32 v89, v89
	v_exp_f32_e32 v90, v90
	v_exp_f32_e32 v91, v91
	ds_read_b128 v[224:227], v159 offset:160
	s_waitcnt lgkmcnt(12)
	v_mfma_f32_32x32x16_bf16 v[64:79], v[4:7], v[80:83], v[64:79]
	v_exp_f32_e32 v92, v92
	v_exp_f32_e32 v93, v93
	v_exp_f32_e32 v94, v94
	s_waitcnt lgkmcnt(10)
	v_mfma_f32_32x32x16_bf16 v[48:63], v[8:11], v[80:83], v[48:63]
	v_exp_f32_e32 v95, v95
	v_add_f32_e32 v0, v0, v88
	v_add_f32_e32 v0, v0, v89
	v_add_f32_e32 v0, v0, v90
	v_add_f32_e32 v0, v0, v91
	s_waitcnt lgkmcnt(8)
	v_add_f32_e32 v0, v0, v92
	v_add_f32_e32 v0, v0, v93
	v_add_f32_e32 v0, v0, v94
	v_add_f32_e32 v0, v0, v95
	v_cvt_pk_bf16_f32 v88, v88, v89
	v_cvt_pk_bf16_f32 v89, v90, v91
	v_cvt_pk_bf16_f32 v90, v92, v93
	v_cvt_pk_bf16_f32 v91, v94, v95
	s_nop 1
	v_mfma_f32_32x32x16_bf16 v[64:79], v[12:15], v[88:91], v[64:79]
	s_cmp_eq_u32 s12, 0
	s_cbranch_scc1 .Lattn_21_B_nosub
	v_sub_f32_e32 v96, v96, v201
	v_sub_f32_e32 v97, v97, v201
	v_sub_f32_e32 v98, v98, v201
	v_sub_f32_e32 v99, v99, v201
	v_sub_f32_e32 v100, v100, v201
	v_sub_f32_e32 v101, v101, v201
	v_sub_f32_e32 v102, v102, v201
	v_sub_f32_e32 v103, v103, v201
	v_sub_f32_e32 v104, v104, v201
	v_sub_f32_e32 v105, v105, v201
	v_sub_f32_e32 v106, v106, v201
	v_sub_f32_e32 v107, v107, v201
	v_sub_f32_e32 v108, v108, v201
	v_sub_f32_e32 v109, v109, v201
	v_sub_f32_e32 v110, v110, v201
	v_sub_f32_e32 v111, v111, v201

; #define MFMA32(a, b, c) __builtin_amdgcn_mfma_f32_32x32x16_bf16((a), (b), (c), 0, 0, 0)
; DI void attn_item(const Ctx& c, int item, bf16* lds) {
;     ...
;       if (__builtin_amdgcn_ballot_w64(m[qs] != 0.f) != 0ull) {
; #pragma unroll
;         for (int i = 0; i < 16; ++i) { st[0][i] -= m[qs]; st[1][i] -= m[qs]; }
;       }
;       float mx = st[0][0];
; #pragma unroll
;       for (int i = 1; i < 16; ++i) mx = fmaxf(mx, st[0][i]);
; #pragma unroll
;       for (int i = 0; i < 16; ++i) mx = fmaxf(mx, st[1][i]);
;       mx = xhalf_max(mx);
;       if (__builtin_amdgcn_ballot_w64((kt == 0) ? (fabsf(mx) > 16.f) : (mx > 16.f)) != 0ull) {
;         const float d = (kt == 0) ? mx : fmaxf(mx, 0.f);
;         const float alpha = __builtin_amdgcn_exp2f(-d);
;         m[qs] += d; lsum[qs] *= alpha;
; #pragma unroll
;         for (int i = 0; i < 16; ++i) { ot[qs][0][i] *= alpha; ot[qs][1][i] *= alpha; st[0][i] -= d; st[1][i] -= d; }
;       }
;       float ps = 0.f;
; #pragma unroll
;       for (int sp = 0; sp < 4; ++sp) {
;         const int mt = sp >> 1, s2 = sp & 1;
;         float e[8];
; #pragma unroll
;         for (int j = 0; j < 8; ++j) { e[j] = __builtin_amdgcn_exp2f(st[mt][8 * s2 + j]); ps += e[j]; }
;         u32x4 pk;
;         pk[0] = pk2(e[0], e[1]); pk[1] = pk2(e[2], e[3]); pk[2] = pk2(e[4], e[5]); pk[3] = pk2(e[6], e[7]);
;         const bf16x8 pf = __builtin_bit_cast(bf16x8, pk);
; #pragma unroll
;         for (int vt = 0; vt < 2; ++vt) {
;           const bf16* vp = Vs + (32 * vt + r) * AV_LD + 32 * mt + 16 * s2 + 4 * hh;
;           const s16x4 lo = *(const s16x4*)(vp), hi = *(const s16x4*)(vp + 8);
;           const bf16x8 a = __builtin_shufflevector(lo, hi, 0, 1, 2, 3, 4, 5, 6, 7);
;           ot[qs][vt] = MFMA32(a, pf, ot[qs][vt]);
;         }
;       }
;       lsum[qs] += ps;
;     }
;   }
.Lattn_21_B_back:
	s_waitcnt lgkmcnt(5)
	v_mfma_f32_32x32x16_bf16 v[80:95], v[204:207], v[112:115], 0
	v_exp_f32_e32 v96, v96
	v_exp_f32_e32 v97, v97
	v_exp_f32_e32 v98, v98
	s_waitcnt lgkmcnt(4)
	v_mfma_f32_32x32x16_bf16 v[80:95], v[208:211], v[116:119], v[80:95]
	v_exp_f32_e32 v99, v99
	v_exp_f32_e32 v100, v100
	v_exp_f32_e32 v101, v101
	s_waitcnt lgkmcnt(3)
	v_mfma_f32_32x32x16_bf16 v[80:95], v[212:215], v[120:123], v[80:95]
	v_exp_f32_e32 v102, v102
	v_exp_f32_e32 v103, v103
	v_add_f32_e32 v203, v203, v96
	v_add_f32_e32 v203, v203, v97
	s_waitcnt lgkmcnt(2)
	v_mfma_f32_32x32x16_bf16 v[80:95], v[216:219], v[124:127], v[80:95]
	v_add_f32_e32 v203, v203, v98
	v_add_f32_e32 v203, v203, v99
	v_add_f32_e32 v203, v203, v100
	v_add_f32_e32 v203, v203, v101
	v_add_f32_e32 v203, v203, v102
	v_add_f32_e32 v203, v203, v103
	s_waitcnt lgkmcnt(1)
	v_mfma_f32_32x32x16_bf16 v[80:95], v[220:223], v[128:131], v[80:95]
	v_cvt_pk_bf16_f32 v96, v96, v97
	v_cvt_pk_bf16_f32 v97, v98, v99
	v_cvt_pk_bf16_f32 v98, v100, v101
	v_cvt_pk_bf16_f32 v99, v102, v103
	v_exp_f32_e32 v104, v104
	s_waitcnt lgkmcnt(0)
	v_mfma_f32_32x32x16_bf16 v[80:95], v[224:227], v[132:135], v[80:95]
	v_exp_f32_e32 v105, v105
	v_exp_f32_e32 v106, v106
	v_exp_f32_e32 v107, v107
	s_add_i32 s1, s1, 1
	v_exp_f32_e32 v108, v108
	v_exp_f32_e32 v109, v109
	v_exp_f32_e32 v110, v110
	v_exp_f32_e32 v111, v111
	v_add_f32_e32 v203, v203, v104
	v_add_f32_e32 v203, v203, v105
	v_add_f32_e32 v203, v203, v106
	v_add_f32_e32 v203, v203, v107
	v_add_f32_e32 v203, v203, v108
	v_add_f32_e32 v203, v203, v109
	v_add_f32_e32 v203, v203, v110
	v_add_f32_e32 v203, v203, v111
	v_cvt_pk_bf16_f32 v104, v104, v105
	v_cvt_pk_bf16_f32 v105, v106, v107
	v_cvt_pk_bf16_f32 v106, v108, v109
	v_cvt_pk_bf16_f32 v107, v110, v111
	s_cmpk_lg_i32 s1, 0x84
	s_cbranch_scc1 .Lattn_loop
	v_mfma_f32_32x32x16_bf16 v[32:47], v[4:7], v[96:99], v[32:47]
	v_mfma_f32_32x32x16_bf16 v[16:31], v[8:11], v[96:99], v[16:31]
	v_mfma_f32_32x32x16_bf16 v[32:47], v[12:15], v[104:107], v[32:47]
	v_mfma_f32_32x32x16_bf16 v[16:31], v[192:195], v[104:107], v[16:31]
	v_mov_b32_e32 v8, v203
	s_setprio 0
	s_waitcnt vmcnt(0)
	s_branch .LBB0_820
.Lattn_00_A_rare:
	s_mov_b32 s9, 1
	v_mov_b32_e32 v191, v185
	s_nop 1
	v_permlane32_swap_b32_e32 v185, v191
	v_max_f32_e32 v185, v185, v191
	v_max_f32_e32 v197, 0, v185
	v_cndmask_b32_e64 v197, v197, v185, s[4:5]
	v_exp_f32_e64 v198, -v197
	v_add_f32_e32 v2, v2, v197
	v_sub_f32_e32 v80, v80, v197
	v_sub_f32_e32 v81, v81, v197
	v_sub_f32_e32 v82, v82, v197
	v_sub_f32_e32 v83, v83, v197
	v_sub_f32_e32 v84, v84, v197
	v_sub_f32_e32 v85, v85, v197
	v_sub_f32_e32 v86, v86, v197
	v_sub_f32_e32 v87, v87, v197
	v_sub_f32_e32 v88, v88, v197
	v_sub_f32_e32 v89, v89, v197
	v_sub_f32_e32 v90, v90, v197
	v_sub_f32_e32 v91, v91, v197
	v_sub_f32_e32 v92, v92, v197
	v_sub_f32_e32 v93, v93, v197
	v_sub_f32_e32 v94, v94, v197
	v_sub_f32_e32 v95, v95, v197
	v_mul_f32_e32 v0, v0, v198
	v_mul_f32_e32 v64, v64, v198
	v_mul_f32_e32 v65, v65, v198
	v_mul_f32_e32 v66, v66, v198
	v_mul_f32_e32 v67, v67, v198
	v_mul_f32_e32 v68, v68, v198
	v_mul_f32_e32 v69, v69, v198
	v_mul_f32_e32 v70, v70, v198
	v_mul_f32_e32 v71, v71, v198
	v_mul_f32_e32 v72, v72, v198
	v_mul_f32_e32 v73, v73, v198
	v_mul_f32_e32 v74, v74, v198
	v_mul_f32_e32 v75, v75, v198
	v_mul_f32_e32 v76, v76, v198
	v_mul_f32_e32 v77, v77, v198
	v_mul_f32_e32 v78, v78, v198
	v_mul_f32_e32 v79, v79, v198
	v_mul_f32_e32 v48, v48, v198
	v_mul_f32_e32 v49, v49, v198
	v_mul_f32_e32 v50, v50, v198
	v_mul_f32_e32 v51, v51, v198
	v_mul_f32_e32 v52, v52, v198
	v_mul_f32_e32 v53, v53, v198
	v_mul_f32_e32 v54, v54, v198
	v_mul_f32_e32 v55, v55, v198
	v_mul_f32_e32 v56, v56, v198
	v_mul_f32_e32 v57, v57, v198
	v_mul_f32_e32 v58, v58, v198
	v_mul_f32_e32 v59, v59, v198
	v_mul_f32_e32 v60, v60, v198
	v_mul_f32_e32 v61, v61, v198
	v_mul_f32_e32 v62, v62, v198
	v_mul_f32_e32 v63, v63, v198
	s_branch .Lattn_00_A_back
; DI void attn_item(const Ctx& c, int item, bf16* lds) {
;     ...
;       mx = xhalf_max(mx);
;       if (__builtin_amdgcn_ballot_w64((kt == 0) ? (fabsf(mx) > 16.f) : (mx > 16.f)) != 0ull) {
;         const float d = (kt == 0) ? mx : fmaxf(mx, 0.f);
;         const float alpha = __builtin_amdgcn_exp2f(-d);
;         m[qs] += d; lsum[qs] *= alpha;
; #pragma unroll
;         for (int i = 0; i < 16; ++i) { ot[qs][0][i] *= alpha; ot[qs][1][i] *= alpha; st[0][i] -= d; st[1][i] -= d; }
;       }
.Lattn_00_B_rare:
	s_mov_b32 s12, 1
	v_mov_b32_e32 v191, v185
	s_nop 1
	v_permlane32_swap_b32_e32 v185, v191
	v_max_f32_e32 v185, v185, v191
	v_max_f32_e32 v197, 0, v185
	v_cndmask_b32_e64 v197, v197, v185, s[4:5]
	v_exp_f32_e64 v198, -v197
	v_add_f32_e32 v201, v201, v197
	v_sub_f32_e32 v96, v96, v197
	v_sub_f32_e32 v97, v97, v197
	v_sub_f32_e32 v98, v98, v197
	v_sub_f32_e32 v99, v99, v197
	v_sub_f32_e32 v100, v100, v197
	v_sub_f32_e32 v101, v101, v197
	v_sub_f32_e32 v102, v102, v197
	v_sub_f32_e32 v103, v103, v197
	v_sub_f32_e32 v104, v104, v197
	v_sub_f32_e32 v105, v105, v197
	v_sub_f32_e32 v106, v106, v197
	v_sub_f32_e32 v107, v107, v197
	v_sub_f32_e32 v108, v108, v197
	v_sub_f32_e32 v109, v109, v197
	v_sub_f32_e32 v110, v110, v197
	v_sub_f32_e32 v111, v111, v197
	v_mul_f32_e32 v203, v203, v198
	v_mul_f32_e32 v32, v32, v198
	v_mul_f32_e32 v33, v33, v198
	v_mul_f32_e32 v34, v34, v198
	v_mul_f32_e32 v35, v35, v198
	v_mul_f32_e32 v36, v36, v198
	v_mul_f32_e32 v37, v37, v198
	v_mul_f32_e32 v38, v38, v198
	v_mul_f32_e32 v39, v39, v198
	v_mul_f32_e32 v40, v40, v198
	v_mul_f32_e32 v41, v41, v198
	v_mul_f32_e32 v42, v42, v198
	v_mul_f32_e32 v43, v43, v198
	v_mul_f32_e32 v44, v44, v198
	v_mul_f32_e32 v45, v45, v198
	v_mul_f32_e32 v46, v46, v198
	v_mul_f32_e32 v47, v47, v198
	v_mul_f32_e32 v16, v16, v198
	v_mul_f32_e32 v17, v17, v198
	v_mul_f32_e32 v18, v18, v198
	v_mul_f32_e32 v19, v19, v198
	v_mul_f32_e32 v20, v20, v198
	v_mul_f32_e32 v21, v21, v198
	v_mul_f32_e32 v22, v22, v198
	v_mul_f32_e32 v23, v23, v198
	v_mul_f32_e32 v24, v24, v198
	v_mul_f32_e32 v25, v25, v198
	v_mul_f32_e32 v26, v26, v198
	v_mul_f32_e32 v27, v27, v198
	v_mul_f32_e32 v28, v28, v198
	v_mul_f32_e32 v29, v29, v198
	v_mul_f32_e32 v30, v30, v198
	v_mul_f32_e32 v31, v31, v198
	s_branch .Lattn_00_B_back
.Lattn_01_A_rare:
	s_mov_b32 s9, 1
	v_mov_b32_e32 v191, v185
	s_nop 1
	v_permlane32_swap_b32_e32 v185, v191
	v_max_f32_e32 v185, v185, v191
	v_max_f32_e32 v197, 0, v185
	v_exp_f32_e64 v198, -v197
	v_add_f32_e32 v2, v2, v197
	v_sub_f32_e32 v80, v80, v197
	v_sub_f32_e32 v81, v81, v197
	v_sub_f32_e32 v82, v82, v197
	v_sub_f32_e32 v83, v83, v197
	v_sub_f32_e32 v84, v84, v197
	v_sub_f32_e32 v85, v85, v197
	v_sub_f32_e32 v86, v86, v197
	v_sub_f32_e32 v87, v87, v197
	v_sub_f32_e32 v88, v88, v197
	v_sub_f32_e32 v89, v89, v197
	v_sub_f32_e32 v90, v90, v197
	v_sub_f32_e32 v91, v91, v197
	v_sub_f32_e32 v92, v92, v197
	v_sub_f32_e32 v93, v93, v197
	v_sub_f32_e32 v94, v94, v197
	v_sub_f32_e32 v95, v95, v197
	v_mul_f32_e32 v0, v0, v198
	v_mul_f32_e32 v64, v64, v198
	v_mul_f32_e32 v65, v65, v198
	v_mul_f32_e32 v66, v66, v198
	v_mul_f32_e32 v67, v67, v198
	v_mul_f32_e32 v68, v68, v198
	v_mul_f32_e32 v69, v69, v198
	v_mul_f32_e32 v70, v70, v198
	v_mul_f32_e32 v71, v71, v198
	v_mul_f32_e32 v72, v72, v198
	v_mul_f32_e32 v73, v73, v198
	v_mul_f32_e32 v74, v74, v198
	v_mul_f32_e32 v75, v75, v198
	v_mul_f32_e32 v76, v76, v198
	v_mul_f32_e32 v77, v77, v198
	v_mul_f32_e32 v78, v78, v198
	v_mul_f32_e32 v79, v79, v198
	v_mul_f32_e32 v48, v48, v198
	v_mul_f32_e32 v49, v49, v198
	v_mul_f32_e32 v50, v50, v198
	v_mul_f32_e32 v51, v51, v198
	v_mul_f32_e32 v52, v52, v198
	v_mul_f32_e32 v53, v53, v198
	v_mul_f32_e32 v54, v54, v198
	v_mul_f32_e32 v55, v55, v198
	v_mul_f32_e32 v56, v56, v198
	v_mul_f32_e32 v57, v57, v198
	v_mul_f32_e32 v58, v58, v198
	v_mul_f32_e32 v59, v59, v198
	v_mul_f32_e32 v60, v60, v198
	v_mul_f32_e32 v61, v61, v198
	v_mul_f32_e32 v62, v62, v198
	v_mul_f32_e32 v63, v63, v198
	s_branch .Lattn_01_A_back
.Lattn_01_B_rare:
	s_mov_b32 s12, 1
	v_mov_b32_e32 v191, v185
	s_nop 1
	v_permlane32_swap_b32_e32 v185, v191
	v_max_f32_e32 v185, v185, v191
	v_max_f32_e32 v197, 0, v185
	v_exp_f32_e64 v198, -v197
	v_add_f32_e32 v201, v201, v197
	v_sub_f32_e32 v96, v96, v197
	v_sub_f32_e32 v97, v97, v197
	v_sub_f32_e32 v98, v98, v197
	v_sub_f32_e32 v99, v99, v197
	v_sub_f32_e32 v100, v100, v197
	v_sub_f32_e32 v101, v101, v197
	v_sub_f32_e32 v102, v102, v197
	v_sub_f32_e32 v103, v103, v197
	v_sub_f32_e32 v104, v104, v197
	v_sub_f32_e32 v105, v105, v197
	v_sub_f32_e32 v106, v106, v197
	v_sub_f32_e32 v107, v107, v197
	v_sub_f32_e32 v108, v108, v197
	v_sub_f32_e32 v109, v109, v197
	v_sub_f32_e32 v110, v110, v197
	v_sub_f32_e32 v111, v111, v197
	v_mul_f32_e32 v203, v203, v198
	v_mul_f32_e32 v32, v32, v198
	v_mul_f32_e32 v33, v33, v198
	v_mul_f32_e32 v34, v34, v198
	v_mul_f32_e32 v35, v35, v198
	v_mul_f32_e32 v36, v36, v198
	v_mul_f32_e32 v37, v37, v198
	v_mul_f32_e32 v38, v38, v198
	v_mul_f32_e32 v39, v39, v198
	v_mul_f32_e32 v40, v40, v198
	v_mul_f32_e32 v41, v41, v198
	v_mul_f32_e32 v42, v42, v198
	v_mul_f32_e32 v43, v43, v198
	v_mul_f32_e32 v44, v44, v198
	v_mul_f32_e32 v45, v45, v198
	v_mul_f32_e32 v46, v46, v198
	v_mul_f32_e32 v47, v47, v198
	v_mul_f32_e32 v16, v16, v198
	v_mul_f32_e32 v17, v17, v198
	v_mul_f32_e32 v18, v18, v198
	v_mul_f32_e32 v19, v19, v198
	v_mul_f32_e32 v20, v20, v198
	v_mul_f32_e32 v21, v21, v198
	v_mul_f32_e32 v22, v22, v198
	v_mul_f32_e32 v23, v23, v198
	v_mul_f32_e32 v24, v24, v198
	v_mul_f32_e32 v25, v25, v198
	v_mul_f32_e32 v26, v26, v198
	v_mul_f32_e32 v27, v27, v198
	v_mul_f32_e32 v28, v28, v198
	v_mul_f32_e32 v29, v29, v198
	v_mul_f32_e32 v30, v30, v198
	v_mul_f32_e32 v31, v31, v198
	s_branch .Lattn_01_B_back
